# v27 = v26 with the B (weight) k-tile loads issued before the A loads in the MT4 k-loops
# speedup vs baseline: 1.0109x; 1.0052x over previous
.LBB0_302:
	ds_read_b128 v[216:219], v176 offset:36864
	ds_read_b128 v[200:203], v188
	ds_read_b128 v[220:223], v176 offset:41472
	ds_read_b128 v[204:207], v188 offset:4608
	ds_read_b128 v[208:211], v188 offset:9216
	ds_read_b128 v[212:215], v187
	s_waitcnt lgkmcnt(4)
	v_mfma_f32_32x32x16_bf16 v[112:127], v[200:203], v[216:219], v[112:127]
	ds_read_b128 v[240:243], v176 offset:36896
	global_load_dwordx4 v[140:143], v190, s[42:43]
	s_waitcnt lgkmcnt(4)
	v_mfma_f32_32x32x16_bf16 v[96:111], v[200:203], v[220:223], v[96:111]
	ds_read_b128 v[224:227], v188 offset:32
	global_load_dwordx4 v[160:163], v191, s[42:43]
	s_waitcnt lgkmcnt(4)
	v_mfma_f32_32x32x16_bf16 v[80:95], v[204:207], v[216:219], v[80:95]
	ds_read_b128 v[244:247], v176 offset:41504
	global_load_dwordx4 v[168:171], v192, s[42:43]
	s_waitcnt lgkmcnt(5)
	v_mfma_f32_32x32x16_bf16 v[64:79], v[204:207], v[220:223], v[64:79]
	ds_read_b128 v[228:231], v188 offset:4640
	global_load_dwordx4 v[172:175], v193, s[42:43]
	s_waitcnt lgkmcnt(5)
	v_mfma_f32_32x32x16_bf16 v[48:63], v[208:211], v[216:219], v[48:63]
	ds_read_b128 v[232:235], v188 offset:9248
	global_load_dwordx4 v[164:167], v190, s[40:41]
	s_waitcnt lgkmcnt(6)
	v_mfma_f32_32x32x16_bf16 v[32:47], v[208:211], v[220:223], v[32:47]
	ds_read_b128 v[236:239], v187 offset:32
	global_load_dwordx4 v[128:131], v191, s[40:41]
	s_waitcnt lgkmcnt(6)
	v_mfma_f32_32x32x16_bf16 v[16:31], v[212:215], v[216:219], v[16:31]
	global_load_dwordx4 v[132:135], v192, s[40:41]
	s_waitcnt lgkmcnt(6)
	v_mfma_f32_32x32x16_bf16 v[0:15], v[212:215], v[220:223], v[0:15]
	global_load_dwordx4 v[136:139], v193, s[40:41]
	s_waitcnt lgkmcnt(4)
	v_mfma_f32_32x32x16_bf16 v[112:127], v[224:227], v[240:243], v[112:127]
	ds_read_b128 v[200:203], v188 offset:64
	global_load_dwordx4 v[144:147], v194, s[40:41]
	s_waitcnt lgkmcnt(4)
	v_mfma_f32_32x32x16_bf16 v[96:111], v[224:227], v[244:247], v[96:111]
	ds_read_b128 v[204:207], v188 offset:4672
	global_load_dwordx4 v[148:151], v195, s[40:41]
	s_waitcnt lgkmcnt(4)
	v_mfma_f32_32x32x16_bf16 v[80:95], v[228:231], v[240:243], v[80:95]
	ds_read_b128 v[208:211], v188 offset:9280
	global_load_dwordx4 v[152:155], v196, s[40:41]
	s_waitcnt lgkmcnt(5)
	v_mfma_f32_32x32x16_bf16 v[64:79], v[228:231], v[244:247], v[64:79]
	ds_read_b128 v[212:215], v187 offset:64
	global_load_dwordx4 v[156:159], v197, s[40:41]
	s_add_u32 s40, s40, 0x80
	s_addc_u32 s41, s41, 0
	s_add_u32 s42, s42, 0x80
	s_addc_u32 s43, s43, 0
	s_add_u32 s16, s16, 0x80
	s_waitcnt lgkmcnt(5)
	v_mfma_f32_32x32x16_bf16 v[48:63], v[232:235], v[240:243], v[48:63]
	ds_read_b128 v[216:219], v176 offset:36928
	s_waitcnt lgkmcnt(6)
	v_mfma_f32_32x32x16_bf16 v[32:47], v[232:235], v[244:247], v[32:47]
	ds_read_b128 v[220:223], v176 offset:41536
	s_waitcnt lgkmcnt(6)
	v_mfma_f32_32x32x16_bf16 v[16:31], v[236:239], v[240:243], v[16:31]
	s_waitcnt lgkmcnt(6)
	v_mfma_f32_32x32x16_bf16 v[0:15], v[236:239], v[244:247], v[0:15]
	s_waitcnt lgkmcnt(1)
	v_mfma_f32_32x32x16_bf16 v[112:127], v[200:203], v[216:219], v[112:127]
	ds_read_b128 v[224:227], v188 offset:96
	s_waitcnt lgkmcnt(1)
	v_mfma_f32_32x32x16_bf16 v[96:111], v[200:203], v[220:223], v[96:111]
	ds_read_b128 v[228:231], v188 offset:4704
	s_waitcnt lgkmcnt(3)
	v_mfma_f32_32x32x16_bf16 v[80:95], v[204:207], v[216:219], v[80:95]
	ds_read_b128 v[232:235], v188 offset:9312
	s_waitcnt lgkmcnt(3)
	v_mfma_f32_32x32x16_bf16 v[64:79], v[204:207], v[220:223], v[64:79]
	ds_read_b128 v[236:239], v187 offset:96
	s_waitcnt lgkmcnt(5)
	v_mfma_f32_32x32x16_bf16 v[48:63], v[208:211], v[216:219], v[48:63]
	ds_read_b128 v[240:243], v176 offset:36960
	s_waitcnt lgkmcnt(5)
	v_mfma_f32_32x32x16_bf16 v[32:47], v[208:211], v[220:223], v[32:47]
	ds_read_b128 v[244:247], v176 offset:41568
	s_waitcnt lgkmcnt(7)
	v_mfma_f32_32x32x16_bf16 v[16:31], v[212:215], v[216:219], v[16:31]
	s_waitcnt lgkmcnt(6)
	v_mfma_f32_32x32x16_bf16 v[0:15], v[212:215], v[220:223], v[0:15]
	s_waitcnt lgkmcnt(0)
	s_barrier
	s_waitcnt vmcnt(0)
	s_waitcnt lgkmcnt(1)
	v_mfma_f32_32x32x16_bf16 v[112:127], v[224:227], v[240:243], v[112:127]
	ds_write_b128 v189, v[164:167]
	ds_write_b128 v189, v[128:131] offset:4608
	s_waitcnt lgkmcnt(2)
	v_mfma_f32_32x32x16_bf16 v[96:111], v[224:227], v[244:247], v[96:111]
	ds_write_b128 v189, v[132:135] offset:9216
	s_waitcnt lgkmcnt(4)
	v_mfma_f32_32x32x16_bf16 v[80:95], v[228:231], v[240:243], v[80:95]
	ds_write_b128 v189, v[136:139] offset:13824
	ds_write_b128 v189, v[144:147] offset:18432
	s_waitcnt lgkmcnt(5)
	v_mfma_f32_32x32x16_bf16 v[64:79], v[228:231], v[244:247], v[64:79]
	ds_write_b128 v189, v[148:151] offset:23040
	s_waitcnt lgkmcnt(7)
	v_mfma_f32_32x32x16_bf16 v[48:63], v[232:235], v[240:243], v[48:63]
	ds_write_b128 v189, v[152:155] offset:27648
	ds_write_b128 v189, v[156:159] offset:32256
	s_waitcnt lgkmcnt(8)
	v_mfma_f32_32x32x16_bf16 v[32:47], v[232:235], v[244:247], v[32:47]
	ds_write_b128 v189, v[140:143] offset:36864
	s_waitcnt lgkmcnt(10)
	v_mfma_f32_32x32x16_bf16 v[16:31], v[236:239], v[240:243], v[16:31]
	ds_write_b128 v189, v[160:163] offset:41472
	ds_write_b128 v189, v[168:171] offset:46080
	s_waitcnt lgkmcnt(11)
	v_mfma_f32_32x32x16_bf16 v[0:15], v[236:239], v[244:247], v[0:15]
	ds_write_b128 v189, v[172:175] offset:50688
	s_waitcnt lgkmcnt(0)
	s_barrier
	s_cmpk_lg_i32 s16, 0x780
	s_cbranch_scc1 .LBB0_302
	ds_read_b128 v[216:219], v176 offset:36864
	ds_read_b128 v[200:203], v188
	ds_read_b128 v[220:223], v176 offset:41472
	ds_read_b128 v[204:207], v188 offset:4608
	ds_read_b128 v[208:211], v188 offset:9216
	ds_read_b128 v[212:215], v187
	s_waitcnt lgkmcnt(4)
	v_mfma_f32_32x32x16_bf16 v[112:127], v[200:203], v[216:219], v[112:127]
	ds_read_b128 v[240:243], v176 offset:36896
	s_waitcnt lgkmcnt(4)
	v_mfma_f32_32x32x16_bf16 v[96:111], v[200:203], v[220:223], v[96:111]
	ds_read_b128 v[224:227], v188 offset:32
	s_waitcnt lgkmcnt(4)
	v_mfma_f32_32x32x16_bf16 v[80:95], v[204:207], v[216:219], v[80:95]
	ds_read_b128 v[244:247], v176 offset:41504
	s_waitcnt lgkmcnt(5)
	v_mfma_f32_32x32x16_bf16 v[64:79], v[204:207], v[220:223], v[64:79]
	ds_read_b128 v[228:231], v188 offset:4640
	s_waitcnt lgkmcnt(5)
	v_mfma_f32_32x32x16_bf16 v[48:63], v[208:211], v[216:219], v[48:63]
	ds_read_b128 v[232:235], v188 offset:9248
	s_waitcnt lgkmcnt(6)
	v_mfma_f32_32x32x16_bf16 v[32:47], v[208:211], v[220:223], v[32:47]
	ds_read_b128 v[236:239], v187 offset:32
	s_waitcnt lgkmcnt(6)
	v_mfma_f32_32x32x16_bf16 v[16:31], v[212:215], v[216:219], v[16:31]
	s_waitcnt lgkmcnt(6)
	v_mfma_f32_32x32x16_bf16 v[0:15], v[212:215], v[220:223], v[0:15]
	s_waitcnt lgkmcnt(4)
	v_mfma_f32_32x32x16_bf16 v[112:127], v[224:227], v[240:243], v[112:127]
	ds_read_b128 v[200:203], v188 offset:64
	s_waitcnt lgkmcnt(4)
	v_mfma_f32_32x32x16_bf16 v[96:111], v[224:227], v[244:247], v[96:111]
	ds_read_b128 v[204:207], v188 offset:4672
	s_waitcnt lgkmcnt(4)
	v_mfma_f32_32x32x16_bf16 v[80:95], v[228:231], v[240:243], v[80:95]
	ds_read_b128 v[208:211], v188 offset:9280
	s_waitcnt lgkmcnt(5)
	v_mfma_f32_32x32x16_bf16 v[64:79], v[228:231], v[244:247], v[64:79]
	ds_read_b128 v[212:215], v187 offset:64
	s_waitcnt lgkmcnt(5)
	v_mfma_f32_32x32x16_bf16 v[48:63], v[232:235], v[240:243], v[48:63]
	ds_read_b128 v[216:219], v176 offset:36928
	s_waitcnt lgkmcnt(6)
	v_mfma_f32_32x32x16_bf16 v[32:47], v[232:235], v[244:247], v[32:47]
	ds_read_b128 v[220:223], v176 offset:41536
	s_waitcnt lgkmcnt(6)
	v_mfma_f32_32x32x16_bf16 v[16:31], v[236:239], v[240:243], v[16:31]
	s_waitcnt lgkmcnt(6)
	v_mfma_f32_32x32x16_bf16 v[0:15], v[236:239], v[244:247], v[0:15]
	s_waitcnt lgkmcnt(1)
	v_mfma_f32_32x32x16_bf16 v[112:127], v[200:203], v[216:219], v[112:127]
	ds_read_b128 v[224:227], v188 offset:96
	s_waitcnt lgkmcnt(1)
	v_mfma_f32_32x32x16_bf16 v[96:111], v[200:203], v[220:223], v[96:111]
	ds_read_b128 v[228:231], v188 offset:4704
	s_waitcnt lgkmcnt(3)
	v_mfma_f32_32x32x16_bf16 v[80:95], v[204:207], v[216:219], v[80:95]
	ds_read_b128 v[232:235], v188 offset:9312
	s_waitcnt lgkmcnt(3)
	v_mfma_f32_32x32x16_bf16 v[64:79], v[204:207], v[220:223], v[64:79]
	ds_read_b128 v[236:239], v187 offset:96
	s_waitcnt lgkmcnt(5)
	v_mfma_f32_32x32x16_bf16 v[48:63], v[208:211], v[216:219], v[48:63]
	ds_read_b128 v[240:243], v176 offset:36960
	s_waitcnt lgkmcnt(5)
	v_mfma_f32_32x32x16_bf16 v[32:47], v[208:211], v[220:223], v[32:47]
	ds_read_b128 v[244:247], v176 offset:41568
	s_waitcnt lgkmcnt(7)
	v_mfma_f32_32x32x16_bf16 v[16:31], v[212:215], v[216:219], v[16:31]
	s_waitcnt lgkmcnt(6)
	v_mfma_f32_32x32x16_bf16 v[0:15], v[212:215], v[220:223], v[0:15]
	s_waitcnt lgkmcnt(1)
	v_mfma_f32_32x32x16_bf16 v[112:127], v[224:227], v[240:243], v[112:127]
	s_waitcnt lgkmcnt(0)
	v_mfma_f32_32x32x16_bf16 v[96:111], v[224:227], v[244:247], v[96:111]
	s_waitcnt lgkmcnt(1)
	v_mfma_f32_32x32x16_bf16 v[80:95], v[228:231], v[240:243], v[80:95]
	s_waitcnt lgkmcnt(0)
	v_mfma_f32_32x32x16_bf16 v[64:79], v[228:231], v[244:247], v[64:79]
	s_waitcnt lgkmcnt(1)
	v_mfma_f32_32x32x16_bf16 v[48:63], v[232:235], v[240:243], v[48:63]
	s_waitcnt lgkmcnt(0)
	v_mfma_f32_32x32x16_bf16 v[32:47], v[232:235], v[244:247], v[32:47]
	s_waitcnt lgkmcnt(1)
	v_mfma_f32_32x32x16_bf16 v[16:31], v[236:239], v[240:243], v[16:31]
	s_waitcnt lgkmcnt(0)
	v_mfma_f32_32x32x16_bf16 v[0:15], v[236:239], v[244:247], v[0:15]
	s_mul_i32 s44, s12, 0x1240
	s_add_u32 s40, s30, s44
	s_addc_u32 s41, s31, 0
	s_lshl_b32 s44, s8, 1
	s_add_u32 s40, s40, s44
	s_addc_u32 s41, s41, 0
	s_add_u32 s40, s40, 0x7157900
	s_addc_u32 s41, s41, 0
	v_and_b32_e32 v131, 15, v182
	v_lshrrev_b32_e32 v172, 4, v182
	v_lshl_add_u32 v130, v131, 3, s8
	s_movk_i32 s44, 0x920
	v_cmp_gt_u32_e64 s[42:43], s44, v130
	v_mul_u32_u24_e32 v164, 0x1240, v172
	v_lshl_add_u32 v164, v131, 4, v164
	v_add_u32_e32 v165, 0x12400, v164
	v_add_u32_e32 v166, 0x24800, v164
	v_add_u32_e32 v167, 0x36c00, v164
	v_add_u32_e32 v168, 0x92000, v164
	v_add_u32_e32 v169, 0xa4400, v164
	v_add_u32_e32 v170, 0xb6800, v164
	v_add_u32_e32 v171, 0xc8c00, v164
	v_mul_u32_u24_e32 v129, 0x110, v172
	v_lshl_add_u32 v129, v131, 4, v129
	v_lshrrev_b32_e32 v131, 7, v182
	v_bfe_u32 v172, v182, 5, 1
	v_lshlrev_b32_e32 v131, 6, v131
	v_lshl_or_b32 v131, v172, 2, v131
	v_mul_u32_u24_e32 v131, 136, v131
	v_and_b32_e32 v172, 0x5f, v182
	v_add_lshl_u32 v128, v131, v172, 1
	s_barrier
	v_cvt_pk_bf16_f32 v112, v112, v113
	v_cvt_pk_bf16_f32 v114, v114, v115
	v_cvt_pk_bf16_f32 v116, v116, v117
	v_cvt_pk_bf16_f32 v118, v118, v119
	v_cvt_pk_bf16_f32 v120, v120, v121
	v_cvt_pk_bf16_f32 v122, v122, v123
	v_cvt_pk_bf16_f32 v124, v124, v125
	v_cvt_pk_bf16_f32 v126, v126, v127
	v_cvt_pk_bf16_f32 v96, v96, v97
	v_cvt_pk_bf16_f32 v98, v98, v99
	v_cvt_pk_bf16_f32 v100, v100, v101
	v_cvt_pk_bf16_f32 v102, v102, v103
	v_cvt_pk_bf16_f32 v104, v104, v105
	v_cvt_pk_bf16_f32 v106, v106, v107
	v_cvt_pk_bf16_f32 v108, v108, v109
	v_cvt_pk_bf16_f32 v110, v110, v111
	v_cvt_pk_bf16_f32 v80, v80, v81
	v_cvt_pk_bf16_f32 v82, v82, v83
	v_cvt_pk_bf16_f32 v84, v84, v85
	v_cvt_pk_bf16_f32 v86, v86, v87
	v_cvt_pk_bf16_f32 v88, v88, v89
	v_cvt_pk_bf16_f32 v90, v90, v91
	v_cvt_pk_bf16_f32 v92, v92, v93
	v_cvt_pk_bf16_f32 v94, v94, v95
	v_cvt_pk_bf16_f32 v64, v64, v65
	v_cvt_pk_bf16_f32 v66, v66, v67
	v_cvt_pk_bf16_f32 v68, v68, v69
	v_cvt_pk_bf16_f32 v70, v70, v71
	v_cvt_pk_bf16_f32 v72, v72, v73
	v_cvt_pk_bf16_f32 v74, v74, v75
	v_cvt_pk_bf16_f32 v76, v76, v77
	v_cvt_pk_bf16_f32 v78, v78, v79
	ds_write_b16 v128, v112
	ds_write_b16_d16_hi v128, v112 offset:272
	ds_write_b16 v128, v114 offset:544
	ds_write_b16_d16_hi v128, v114 offset:816
	ds_write_b16 v128, v116 offset:2176
	ds_write_b16_d16_hi v128, v116 offset:2448
	ds_write_b16 v128, v118 offset:2720
	ds_write_b16_d16_hi v128, v118 offset:2992
	ds_write_b16 v128, v120 offset:4352
	ds_write_b16_d16_hi v128, v120 offset:4624
	ds_write_b16 v128, v122 offset:4896
	ds_write_b16_d16_hi v128, v122 offset:5168
	ds_write_b16 v128, v124 offset:6528
	ds_write_b16_d16_hi v128, v124 offset:6800
	ds_write_b16 v128, v126 offset:7072
	ds_write_b16_d16_hi v128, v126 offset:7344
	ds_write_b16 v128, v96 offset:64
	ds_write_b16_d16_hi v128, v96 offset:336
	ds_write_b16 v128, v98 offset:608
	ds_write_b16_d16_hi v128, v98 offset:880
	ds_write_b16 v128, v100 offset:2240
	ds_write_b16_d16_hi v128, v100 offset:2512
	ds_write_b16 v128, v102 offset:2784
	ds_write_b16_d16_hi v128, v102 offset:3056
	ds_write_b16 v128, v104 offset:4416
	ds_write_b16_d16_hi v128, v104 offset:4688
	ds_write_b16 v128, v106 offset:4960
	ds_write_b16_d16_hi v128, v106 offset:5232
	ds_write_b16 v128, v108 offset:6592
	ds_write_b16_d16_hi v128, v108 offset:6864
	ds_write_b16 v128, v110 offset:7136
	ds_write_b16_d16_hi v128, v110 offset:7408
	ds_write_b16 v128, v80 offset:8704
	ds_write_b16_d16_hi v128, v80 offset:8976
	ds_write_b16 v128, v82 offset:9248
	ds_write_b16_d16_hi v128, v82 offset:9520
	ds_write_b16 v128, v84 offset:10880
	ds_write_b16_d16_hi v128, v84 offset:11152
	ds_write_b16 v128, v86 offset:11424
	ds_write_b16_d16_hi v128, v86 offset:11696
	ds_write_b16 v128, v88 offset:13056
	ds_write_b16_d16_hi v128, v88 offset:13328
	ds_write_b16 v128, v90 offset:13600
	ds_write_b16_d16_hi v128, v90 offset:13872
	ds_write_b16 v128, v92 offset:15232
	ds_write_b16_d16_hi v128, v92 offset:15504
	ds_write_b16 v128, v94 offset:15776
	ds_write_b16_d16_hi v128, v94 offset:16048
	ds_write_b16 v128, v64 offset:8768
	ds_write_b16_d16_hi v128, v64 offset:9040
	ds_write_b16 v128, v66 offset:9312
	ds_write_b16_d16_hi v128, v66 offset:9584
	ds_write_b16 v128, v68 offset:10944
	ds_write_b16_d16_hi v128, v68 offset:11216
	ds_write_b16 v128, v70 offset:11488
	ds_write_b16_d16_hi v128, v70 offset:11760
	ds_write_b16 v128, v72 offset:13120
	ds_write_b16_d16_hi v128, v72 offset:13392
	ds_write_b16 v128, v74 offset:13664
	ds_write_b16_d16_hi v128, v74 offset:13936
	ds_write_b16 v128, v76 offset:15296
	ds_write_b16_d16_hi v128, v76 offset:15568
	ds_write_b16 v128, v78 offset:15840
	ds_write_b16_d16_hi v128, v78 offset:16112
	s_waitcnt lgkmcnt(0)
	s_barrier
	ds_read_b128 v[132:135], v129
	ds_read_b128 v[136:139], v129 offset:4352
	ds_read_b128 v[140:143], v129 offset:8704
	ds_read_b128 v[144:147], v129 offset:13056
	ds_read_b128 v[148:151], v129 offset:17408
	ds_read_b128 v[152:155], v129 offset:21760
	ds_read_b128 v[156:159], v129 offset:26112
	ds_read_b128 v[160:163], v129 offset:30464
	v_cvt_pk_bf16_f32 v48, v48, v49
	v_cvt_pk_bf16_f32 v50, v50, v51
	v_cvt_pk_bf16_f32 v52, v52, v53
	v_cvt_pk_bf16_f32 v54, v54, v55
	v_cvt_pk_bf16_f32 v56, v56, v57
	v_cvt_pk_bf16_f32 v58, v58, v59
	v_cvt_pk_bf16_f32 v60, v60, v61
	v_cvt_pk_bf16_f32 v62, v62, v63
	v_cvt_pk_bf16_f32 v32, v32, v33
	v_cvt_pk_bf16_f32 v34, v34, v35
	v_cvt_pk_bf16_f32 v36, v36, v37
	v_cvt_pk_bf16_f32 v38, v38, v39
	v_cvt_pk_bf16_f32 v40, v40, v41
	v_cvt_pk_bf16_f32 v42, v42, v43
	v_cvt_pk_bf16_f32 v44, v44, v45
	v_cvt_pk_bf16_f32 v46, v46, v47
	v_cvt_pk_bf16_f32 v16, v16, v17
	v_cvt_pk_bf16_f32 v18, v18, v19
	v_cvt_pk_bf16_f32 v20, v20, v21
	v_cvt_pk_bf16_f32 v22, v22, v23
	v_cvt_pk_bf16_f32 v24, v24, v25
	v_cvt_pk_bf16_f32 v26, v26, v27
	v_cvt_pk_bf16_f32 v28, v28, v29
	v_cvt_pk_bf16_f32 v30, v30, v31
	v_cvt_pk_bf16_f32 v0, v0, v1
	v_cvt_pk_bf16_f32 v2, v2, v3
	v_cvt_pk_bf16_f32 v4, v4, v5
	v_cvt_pk_bf16_f32 v6, v6, v7
	v_cvt_pk_bf16_f32 v8, v8, v9
	v_cvt_pk_bf16_f32 v10, v10, v11
	v_cvt_pk_bf16_f32 v12, v12, v13
	v_cvt_pk_bf16_f32 v14, v14, v15
	s_and_saveexec_b64 s[46:47], s[42:43]
	s_waitcnt lgkmcnt(7)
	global_store_dwordx4 v164, v[132:135], s[40:41]
	s_waitcnt lgkmcnt(6)
	global_store_dwordx4 v165, v[136:139], s[40:41]
	s_waitcnt lgkmcnt(5)
	global_store_dwordx4 v166, v[140:143], s[40:41]
	s_waitcnt lgkmcnt(4)
	global_store_dwordx4 v167, v[144:147], s[40:41]
	s_waitcnt lgkmcnt(3)
	global_store_dwordx4 v168, v[148:151], s[40:41]
	s_waitcnt lgkmcnt(2)
	global_store_dwordx4 v169, v[152:155], s[40:41]
	s_waitcnt lgkmcnt(1)
	global_store_dwordx4 v170, v[156:159], s[40:41]
	s_waitcnt lgkmcnt(0)
	global_store_dwordx4 v171, v[160:163], s[40:41]
	s_or_b64 exec, exec, s[46:47]
	s_barrier
	ds_write_b16 v128, v48
	ds_write_b16_d16_hi v128, v48 offset:272
	ds_write_b16 v128, v50 offset:544
	ds_write_b16_d16_hi v128, v50 offset:816
	ds_write_b16 v128, v52 offset:2176
	ds_write_b16_d16_hi v128, v52 offset:2448
	ds_write_b16 v128, v54 offset:2720
	ds_write_b16_d16_hi v128, v54 offset:2992
	ds_write_b16 v128, v56 offset:4352
	ds_write_b16_d16_hi v128, v56 offset:4624
	ds_write_b16 v128, v58 offset:4896
	ds_write_b16_d16_hi v128, v58 offset:5168
	ds_write_b16 v128, v60 offset:6528
	ds_write_b16_d16_hi v128, v60 offset:6800
	ds_write_b16 v128, v62 offset:7072
	ds_write_b16_d16_hi v128, v62 offset:7344
	ds_write_b16 v128, v32 offset:64
	ds_write_b16_d16_hi v128, v32 offset:336
	ds_write_b16 v128, v34 offset:608
	ds_write_b16_d16_hi v128, v34 offset:880
	ds_write_b16 v128, v36 offset:2240
	ds_write_b16_d16_hi v128, v36 offset:2512
	ds_write_b16 v128, v38 offset:2784
	ds_write_b16_d16_hi v128, v38 offset:3056
	ds_write_b16 v128, v40 offset:4416
	ds_write_b16_d16_hi v128, v40 offset:4688
	ds_write_b16 v128, v42 offset:4960
	ds_write_b16_d16_hi v128, v42 offset:5232
	ds_write_b16 v128, v44 offset:6592
	ds_write_b16_d16_hi v128, v44 offset:6864
	ds_write_b16 v128, v46 offset:7136
	ds_write_b16_d16_hi v128, v46 offset:7408
	ds_write_b16 v128, v16 offset:8704
	ds_write_b16_d16_hi v128, v16 offset:8976
	ds_write_b16 v128, v18 offset:9248
	ds_write_b16_d16_hi v128, v18 offset:9520
	ds_write_b16 v128, v20 offset:10880
	ds_write_b16_d16_hi v128, v20 offset:11152
	ds_write_b16 v128, v22 offset:11424
	ds_write_b16_d16_hi v128, v22 offset:11696
	ds_write_b16 v128, v24 offset:13056
	ds_write_b16_d16_hi v128, v24 offset:13328
	ds_write_b16 v128, v26 offset:13600
	ds_write_b16_d16_hi v128, v26 offset:13872
	ds_write_b16 v128, v28 offset:15232
	ds_write_b16_d16_hi v128, v28 offset:15504
	ds_write_b16 v128, v30 offset:15776
	ds_write_b16_d16_hi v128, v30 offset:16048
	ds_write_b16 v128, v0 offset:8768
	ds_write_b16_d16_hi v128, v0 offset:9040
	ds_write_b16 v128, v2 offset:9312
	ds_write_b16_d16_hi v128, v2 offset:9584
	ds_write_b16 v128, v4 offset:10944
	ds_write_b16_d16_hi v128, v4 offset:11216
	ds_write_b16 v128, v6 offset:11488
	ds_write_b16_d16_hi v128, v6 offset:11760
	ds_write_b16 v128, v8 offset:13120
	ds_write_b16_d16_hi v128, v8 offset:13392
	ds_write_b16 v128, v10 offset:13664
	ds_write_b16_d16_hi v128, v10 offset:13936
	ds_write_b16 v128, v12 offset:15296
	ds_write_b16_d16_hi v128, v12 offset:15568
	ds_write_b16 v128, v14 offset:15840
	ds_write_b16_d16_hi v128, v14 offset:16112
	s_waitcnt lgkmcnt(0)
	s_barrier
	ds_read_b128 v[132:135], v129
	ds_read_b128 v[136:139], v129 offset:4352
	ds_read_b128 v[140:143], v129 offset:8704
	ds_read_b128 v[144:147], v129 offset:13056
	ds_read_b128 v[148:151], v129 offset:17408
	ds_read_b128 v[152:155], v129 offset:21760
	ds_read_b128 v[156:159], v129 offset:26112
	ds_read_b128 v[160:163], v129 offset:30464
	v_add_u32_e32 v164, 0x49000, v164
	v_add_u32_e32 v165, 0x49000, v165
	v_add_u32_e32 v166, 0x49000, v166
	v_add_u32_e32 v167, 0x49000, v167
	v_add_u32_e32 v168, 0x49000, v168
	v_add_u32_e32 v169, 0x49000, v169
	v_add_u32_e32 v170, 0x49000, v170
	v_add_u32_e32 v171, 0x49000, v171
	s_and_saveexec_b64 s[46:47], s[42:43]
	s_waitcnt lgkmcnt(7)
	global_store_dwordx4 v164, v[132:135], s[40:41]
	s_waitcnt lgkmcnt(6)
	global_store_dwordx4 v165, v[136:139], s[40:41]
	s_waitcnt lgkmcnt(5)
	global_store_dwordx4 v166, v[140:143], s[40:41]
	s_waitcnt lgkmcnt(4)
	global_store_dwordx4 v167, v[144:147], s[40:41]
	s_waitcnt lgkmcnt(3)
	global_store_dwordx4 v168, v[148:151], s[40:41]
	s_waitcnt lgkmcnt(2)
	global_store_dwordx4 v169, v[152:155], s[40:41]
	s_waitcnt lgkmcnt(1)
	global_store_dwordx4 v170, v[156:159], s[40:41]
	s_waitcnt lgkmcnt(0)
	global_store_dwordx4 v171, v[160:163], s[40:41]
	s_or_b64 exec, exec, s[46:47]
	s_branch .Lmt4_tail_0

.LBB0_997:
	ds_read_b128 v[216:219], v188 offset:36864
	ds_read_b128 v[200:203], v187
	ds_read_b128 v[220:223], v188 offset:41472
	ds_read_b128 v[204:207], v187 offset:4608
	ds_read_b128 v[208:211], v187 offset:9216
	ds_read_b128 v[212:215], v176
	s_waitcnt lgkmcnt(4)
	v_mfma_f32_32x32x16_bf16 v[112:127], v[200:203], v[216:219], v[112:127]
	ds_read_b128 v[240:243], v188 offset:36896
	global_load_dwordx4 v[152:155], v190, s[40:41]
	s_waitcnt lgkmcnt(4)
	v_mfma_f32_32x32x16_bf16 v[96:111], v[200:203], v[220:223], v[96:111]
	ds_read_b128 v[224:227], v187 offset:32
	global_load_dwordx4 v[164:167], v191, s[40:41]
	s_waitcnt lgkmcnt(4)
	v_mfma_f32_32x32x16_bf16 v[80:95], v[204:207], v[216:219], v[80:95]
	ds_read_b128 v[244:247], v188 offset:41504
	global_load_dwordx4 v[168:171], v192, s[40:41]
	s_waitcnt lgkmcnt(5)
	v_mfma_f32_32x32x16_bf16 v[64:79], v[204:207], v[220:223], v[64:79]
	ds_read_b128 v[228:231], v187 offset:4640
	global_load_dwordx4 v[172:175], v193, s[40:41]
	s_waitcnt lgkmcnt(5)
	v_mfma_f32_32x32x16_bf16 v[48:63], v[208:211], v[216:219], v[48:63]
	ds_read_b128 v[232:235], v187 offset:9248
	global_load_dwordx4 v[160:163], v190, s[38:39]
	s_waitcnt lgkmcnt(6)
	v_mfma_f32_32x32x16_bf16 v[32:47], v[208:211], v[220:223], v[32:47]
	ds_read_b128 v[236:239], v176 offset:32
	global_load_dwordx4 v[128:131], v191, s[38:39]
	s_waitcnt lgkmcnt(6)
	v_mfma_f32_32x32x16_bf16 v[16:31], v[212:215], v[216:219], v[16:31]
	global_load_dwordx4 v[132:135], v192, s[38:39]
	s_waitcnt lgkmcnt(6)
	v_mfma_f32_32x32x16_bf16 v[0:15], v[212:215], v[220:223], v[0:15]
	global_load_dwordx4 v[136:139], v193, s[38:39]
	s_waitcnt lgkmcnt(4)
	v_mfma_f32_32x32x16_bf16 v[112:127], v[224:227], v[240:243], v[112:127]
	ds_read_b128 v[200:203], v187 offset:64
	global_load_dwordx4 v[140:143], v194, s[38:39]
	s_waitcnt lgkmcnt(4)
	v_mfma_f32_32x32x16_bf16 v[96:111], v[224:227], v[244:247], v[96:111]
	ds_read_b128 v[204:207], v187 offset:4672
	global_load_dwordx4 v[144:147], v195, s[38:39]
	s_waitcnt lgkmcnt(4)
	v_mfma_f32_32x32x16_bf16 v[80:95], v[228:231], v[240:243], v[80:95]
	ds_read_b128 v[208:211], v187 offset:9280
	global_load_dwordx4 v[148:151], v196, s[38:39]
	s_waitcnt lgkmcnt(5)
	v_mfma_f32_32x32x16_bf16 v[64:79], v[228:231], v[244:247], v[64:79]
	ds_read_b128 v[212:215], v176 offset:64
	global_load_dwordx4 v[156:159], v197, s[38:39]
	s_add_u32 s38, s38, 0x80
	s_addc_u32 s39, s39, 0
	s_add_u32 s40, s40, 0x80
	s_addc_u32 s41, s41, 0
	s_add_u32 s12, s12, 0x80
	s_waitcnt lgkmcnt(5)
	v_mfma_f32_32x32x16_bf16 v[48:63], v[232:235], v[240:243], v[48:63]
	ds_read_b128 v[216:219], v188 offset:36928
	s_waitcnt lgkmcnt(6)
	v_mfma_f32_32x32x16_bf16 v[32:47], v[232:235], v[244:247], v[32:47]
	ds_read_b128 v[220:223], v188 offset:41536
	s_waitcnt lgkmcnt(6)
	v_mfma_f32_32x32x16_bf16 v[16:31], v[236:239], v[240:243], v[16:31]
	s_waitcnt lgkmcnt(6)
	v_mfma_f32_32x32x16_bf16 v[0:15], v[236:239], v[244:247], v[0:15]
	s_waitcnt lgkmcnt(1)
	v_mfma_f32_32x32x16_bf16 v[112:127], v[200:203], v[216:219], v[112:127]
	ds_read_b128 v[224:227], v187 offset:96
	s_waitcnt lgkmcnt(1)
	v_mfma_f32_32x32x16_bf16 v[96:111], v[200:203], v[220:223], v[96:111]
	ds_read_b128 v[228:231], v187 offset:4704
	s_waitcnt lgkmcnt(3)
	v_mfma_f32_32x32x16_bf16 v[80:95], v[204:207], v[216:219], v[80:95]
	ds_read_b128 v[232:235], v187 offset:9312
	s_waitcnt lgkmcnt(3)
	v_mfma_f32_32x32x16_bf16 v[64:79], v[204:207], v[220:223], v[64:79]
	ds_read_b128 v[236:239], v176 offset:96
	s_waitcnt lgkmcnt(5)
	v_mfma_f32_32x32x16_bf16 v[48:63], v[208:211], v[216:219], v[48:63]
	ds_read_b128 v[240:243], v188 offset:36960
	s_waitcnt lgkmcnt(5)
	v_mfma_f32_32x32x16_bf16 v[32:47], v[208:211], v[220:223], v[32:47]
	ds_read_b128 v[244:247], v188 offset:41568
	s_waitcnt lgkmcnt(7)
	v_mfma_f32_32x32x16_bf16 v[16:31], v[212:215], v[216:219], v[16:31]
	s_waitcnt lgkmcnt(6)
	v_mfma_f32_32x32x16_bf16 v[0:15], v[212:215], v[220:223], v[0:15]
	s_waitcnt lgkmcnt(0)
	s_barrier
	s_waitcnt vmcnt(0)
	s_waitcnt lgkmcnt(1)
	v_mfma_f32_32x32x16_bf16 v[112:127], v[224:227], v[240:243], v[112:127]
	ds_write_b128 v189, v[160:163]
	ds_write_b128 v189, v[128:131] offset:4608
	s_waitcnt lgkmcnt(2)
	v_mfma_f32_32x32x16_bf16 v[96:111], v[224:227], v[244:247], v[96:111]
	ds_write_b128 v189, v[132:135] offset:9216
	s_waitcnt lgkmcnt(4)
	v_mfma_f32_32x32x16_bf16 v[80:95], v[228:231], v[240:243], v[80:95]
	ds_write_b128 v189, v[136:139] offset:13824
	ds_write_b128 v189, v[140:143] offset:18432
	s_waitcnt lgkmcnt(5)
	v_mfma_f32_32x32x16_bf16 v[64:79], v[228:231], v[244:247], v[64:79]
	ds_write_b128 v189, v[144:147] offset:23040
	s_waitcnt lgkmcnt(7)
	v_mfma_f32_32x32x16_bf16 v[48:63], v[232:235], v[240:243], v[48:63]
	ds_write_b128 v189, v[148:151] offset:27648
	ds_write_b128 v189, v[156:159] offset:32256
	s_waitcnt lgkmcnt(8)
	v_mfma_f32_32x32x16_bf16 v[32:47], v[232:235], v[244:247], v[32:47]
	ds_write_b128 v189, v[152:155] offset:36864
	s_waitcnt lgkmcnt(10)
	v_mfma_f32_32x32x16_bf16 v[16:31], v[236:239], v[240:243], v[16:31]
	ds_write_b128 v189, v[164:167] offset:41472
	ds_write_b128 v189, v[168:171] offset:46080
	s_waitcnt lgkmcnt(11)
	v_mfma_f32_32x32x16_bf16 v[0:15], v[236:239], v[244:247], v[0:15]
	ds_write_b128 v189, v[172:175] offset:50688
	s_waitcnt lgkmcnt(0)
	s_barrier
	s_cmpk_lg_i32 s12, 0x780
	s_cbranch_scc1 .LBB0_997
	ds_read_b128 v[216:219], v188 offset:36864
	ds_read_b128 v[200:203], v187
	ds_read_b128 v[220:223], v188 offset:41472
	ds_read_b128 v[204:207], v187 offset:4608
	ds_read_b128 v[208:211], v187 offset:9216
	ds_read_b128 v[212:215], v176
	s_waitcnt lgkmcnt(4)
	v_mfma_f32_32x32x16_bf16 v[112:127], v[200:203], v[216:219], v[112:127]
	ds_read_b128 v[240:243], v188 offset:36896
	s_waitcnt lgkmcnt(4)
	v_mfma_f32_32x32x16_bf16 v[96:111], v[200:203], v[220:223], v[96:111]
	ds_read_b128 v[224:227], v187 offset:32
	s_waitcnt lgkmcnt(4)
	v_mfma_f32_32x32x16_bf16 v[80:95], v[204:207], v[216:219], v[80:95]
	ds_read_b128 v[244:247], v188 offset:41504
	s_waitcnt lgkmcnt(5)
	v_mfma_f32_32x32x16_bf16 v[64:79], v[204:207], v[220:223], v[64:79]
	ds_read_b128 v[228:231], v187 offset:4640
	s_waitcnt lgkmcnt(5)
	v_mfma_f32_32x32x16_bf16 v[48:63], v[208:211], v[216:219], v[48:63]
	ds_read_b128 v[232:235], v187 offset:9248
	s_waitcnt lgkmcnt(6)
	v_mfma_f32_32x32x16_bf16 v[32:47], v[208:211], v[220:223], v[32:47]
	ds_read_b128 v[236:239], v176 offset:32
	s_waitcnt lgkmcnt(6)
	v_mfma_f32_32x32x16_bf16 v[16:31], v[212:215], v[216:219], v[16:31]
	s_waitcnt lgkmcnt(6)
	v_mfma_f32_32x32x16_bf16 v[0:15], v[212:215], v[220:223], v[0:15]
	s_waitcnt lgkmcnt(4)
	v_mfma_f32_32x32x16_bf16 v[112:127], v[224:227], v[240:243], v[112:127]
	ds_read_b128 v[200:203], v187 offset:64
	s_waitcnt lgkmcnt(4)
	v_mfma_f32_32x32x16_bf16 v[96:111], v[224:227], v[244:247], v[96:111]
	ds_read_b128 v[204:207], v187 offset:4672
	s_waitcnt lgkmcnt(4)
	v_mfma_f32_32x32x16_bf16 v[80:95], v[228:231], v[240:243], v[80:95]
	ds_read_b128 v[208:211], v187 offset:9280
	s_waitcnt lgkmcnt(5)
	v_mfma_f32_32x32x16_bf16 v[64:79], v[228:231], v[244:247], v[64:79]
	ds_read_b128 v[212:215], v176 offset:64
	s_waitcnt lgkmcnt(5)
	v_mfma_f32_32x32x16_bf16 v[48:63], v[232:235], v[240:243], v[48:63]
	ds_read_b128 v[216:219], v188 offset:36928
	s_waitcnt lgkmcnt(6)
	v_mfma_f32_32x32x16_bf16 v[32:47], v[232:235], v[244:247], v[32:47]
	ds_read_b128 v[220:223], v188 offset:41536
	s_waitcnt lgkmcnt(6)
	v_mfma_f32_32x32x16_bf16 v[16:31], v[236:239], v[240:243], v[16:31]
	s_waitcnt lgkmcnt(6)
	v_mfma_f32_32x32x16_bf16 v[0:15], v[236:239], v[244:247], v[0:15]
	s_waitcnt lgkmcnt(1)
	v_mfma_f32_32x32x16_bf16 v[112:127], v[200:203], v[216:219], v[112:127]
	ds_read_b128 v[224:227], v187 offset:96
	s_waitcnt lgkmcnt(1)
	v_mfma_f32_32x32x16_bf16 v[96:111], v[200:203], v[220:223], v[96:111]
	ds_read_b128 v[228:231], v187 offset:4704
	s_waitcnt lgkmcnt(3)
	v_mfma_f32_32x32x16_bf16 v[80:95], v[204:207], v[216:219], v[80:95]
	ds_read_b128 v[232:235], v187 offset:9312
	s_waitcnt lgkmcnt(3)
	v_mfma_f32_32x32x16_bf16 v[64:79], v[204:207], v[220:223], v[64:79]
	ds_read_b128 v[236:239], v176 offset:96
	s_waitcnt lgkmcnt(5)
	v_mfma_f32_32x32x16_bf16 v[48:63], v[208:211], v[216:219], v[48:63]
	ds_read_b128 v[240:243], v188 offset:36960
	s_waitcnt lgkmcnt(5)
	v_mfma_f32_32x32x16_bf16 v[32:47], v[208:211], v[220:223], v[32:47]
	ds_read_b128 v[244:247], v188 offset:41568
	s_waitcnt lgkmcnt(7)
	v_mfma_f32_32x32x16_bf16 v[16:31], v[212:215], v[216:219], v[16:31]
	s_waitcnt lgkmcnt(6)
	v_mfma_f32_32x32x16_bf16 v[0:15], v[212:215], v[220:223], v[0:15]
	s_waitcnt lgkmcnt(1)
	v_mfma_f32_32x32x16_bf16 v[112:127], v[224:227], v[240:243], v[112:127]
	s_waitcnt lgkmcnt(0)
	v_mfma_f32_32x32x16_bf16 v[96:111], v[224:227], v[244:247], v[96:111]
	s_waitcnt lgkmcnt(1)
	v_mfma_f32_32x32x16_bf16 v[80:95], v[228:231], v[240:243], v[80:95]
	s_waitcnt lgkmcnt(0)
	v_mfma_f32_32x32x16_bf16 v[64:79], v[228:231], v[244:247], v[64:79]
	s_waitcnt lgkmcnt(1)
	v_mfma_f32_32x32x16_bf16 v[48:63], v[232:235], v[240:243], v[48:63]
	s_waitcnt lgkmcnt(0)
	v_mfma_f32_32x32x16_bf16 v[32:47], v[232:235], v[244:247], v[32:47]
	s_waitcnt lgkmcnt(1)
	v_mfma_f32_32x32x16_bf16 v[16:31], v[236:239], v[240:243], v[16:31]
	s_waitcnt lgkmcnt(0)
	v_mfma_f32_32x32x16_bf16 v[0:15], v[236:239], v[244:247], v[0:15]
	s_mul_i32 s42, s6, 0x2000
	s_add_u32 s44, s30, s42
	s_addc_u32 s45, s31, 0
	s_lshl_b32 s42, s58, 1
	s_add_u32 s44, s44, s42
	s_addc_u32 s45, s45, 0
	s_add_u32 s44, s44, 0x7157900
	s_addc_u32 s45, s45, 0
	s_mov_b32 s43, 1
	v_max_f32_e32 v112, 0, v112
	v_max_f32_e32 v113, 0, v113
	v_mul_f32_e32 v112, v112, v112
	v_mul_f32_e32 v113, v113, v113
	v_cvt_pk_bf16_f32 v190, v112, v113
	v_max_f32_e32 v114, 0, v114
	v_max_f32_e32 v115, 0, v115
	v_mul_f32_e32 v114, v114, v114
	v_mul_f32_e32 v115, v115, v115
	v_cvt_pk_bf16_f32 v191, v114, v115
	v_max_f32_e32 v116, 0, v116
	v_max_f32_e32 v117, 0, v117
	v_mul_f32_e32 v116, v116, v116
	v_mul_f32_e32 v117, v117, v117
	v_cvt_pk_bf16_f32 v192, v116, v117
	v_max_f32_e32 v118, 0, v118
	v_max_f32_e32 v119, 0, v119
	v_mul_f32_e32 v118, v118, v118
	v_mul_f32_e32 v119, v119, v119
	v_cvt_pk_bf16_f32 v193, v118, v119
	v_max_f32_e32 v120, 0, v120
	v_max_f32_e32 v121, 0, v121
	v_mul_f32_e32 v120, v120, v120
	v_mul_f32_e32 v121, v121, v121
	v_cvt_pk_bf16_f32 v194, v120, v121
	v_max_f32_e32 v122, 0, v122
	v_max_f32_e32 v123, 0, v123
	v_mul_f32_e32 v122, v122, v122
	v_mul_f32_e32 v123, v123, v123
	v_cvt_pk_bf16_f32 v195, v122, v123
	v_max_f32_e32 v124, 0, v124
	v_max_f32_e32 v125, 0, v125
	v_mul_f32_e32 v124, v124, v124
	v_mul_f32_e32 v125, v125, v125
	v_cvt_pk_bf16_f32 v196, v124, v125
	v_max_f32_e32 v126, 0, v126
	v_max_f32_e32 v127, 0, v127
	v_mul_f32_e32 v126, v126, v126
	v_mul_f32_e32 v127, v127, v127
	v_cvt_pk_bf16_f32 v197, v126, v127
	v_max_f32_e32 v96, 0, v96
	v_max_f32_e32 v97, 0, v97
	v_mul_f32_e32 v96, v96, v96
	v_mul_f32_e32 v97, v97, v97
	v_cvt_pk_bf16_f32 v198, v96, v97
	v_max_f32_e32 v98, 0, v98
	v_max_f32_e32 v99, 0, v99
	v_mul_f32_e32 v98, v98, v98
	v_mul_f32_e32 v99, v99, v99
	v_cvt_pk_bf16_f32 v199, v98, v99
	v_max_f32_e32 v100, 0, v100
	v_max_f32_e32 v101, 0, v101
	v_mul_f32_e32 v100, v100, v100
	v_mul_f32_e32 v101, v101, v101
	v_cvt_pk_bf16_f32 v200, v100, v101
	v_max_f32_e32 v102, 0, v102
	v_max_f32_e32 v103, 0, v103
	v_mul_f32_e32 v102, v102, v102
	v_mul_f32_e32 v103, v103, v103
	v_cvt_pk_bf16_f32 v201, v102, v103
	v_max_f32_e32 v104, 0, v104
	v_max_f32_e32 v105, 0, v105
	v_mul_f32_e32 v104, v104, v104
	v_mul_f32_e32 v105, v105, v105
	v_cvt_pk_bf16_f32 v202, v104, v105
	v_max_f32_e32 v106, 0, v106
	v_max_f32_e32 v107, 0, v107
	v_mul_f32_e32 v106, v106, v106
	v_mul_f32_e32 v107, v107, v107
	v_cvt_pk_bf16_f32 v203, v106, v107
	v_max_f32_e32 v108, 0, v108
	v_max_f32_e32 v109, 0, v109
	v_mul_f32_e32 v108, v108, v108
	v_mul_f32_e32 v109, v109, v109
	v_cvt_pk_bf16_f32 v204, v108, v109
	v_max_f32_e32 v110, 0, v110
	v_max_f32_e32 v111, 0, v111
	v_mul_f32_e32 v110, v110, v110
	v_mul_f32_e32 v111, v111, v111
	v_cvt_pk_bf16_f32 v205, v110, v111
	v_max_f32_e32 v80, 0, v80
	v_max_f32_e32 v81, 0, v81
	v_mul_f32_e32 v80, v80, v80
	v_mul_f32_e32 v81, v81, v81
	v_cvt_pk_bf16_f32 v206, v80, v81
	v_max_f32_e32 v82, 0, v82
	v_max_f32_e32 v83, 0, v83
	v_mul_f32_e32 v82, v82, v82
	v_mul_f32_e32 v83, v83, v83
	v_cvt_pk_bf16_f32 v207, v82, v83
	v_max_f32_e32 v84, 0, v84
	v_max_f32_e32 v85, 0, v85
	v_mul_f32_e32 v84, v84, v84
	v_mul_f32_e32 v85, v85, v85
	v_cvt_pk_bf16_f32 v208, v84, v85
	v_max_f32_e32 v86, 0, v86
	v_max_f32_e32 v87, 0, v87
	v_mul_f32_e32 v86, v86, v86
	v_mul_f32_e32 v87, v87, v87
	v_cvt_pk_bf16_f32 v209, v86, v87
	v_max_f32_e32 v88, 0, v88
	v_max_f32_e32 v89, 0, v89
	v_mul_f32_e32 v88, v88, v88
	v_mul_f32_e32 v89, v89, v89
	v_cvt_pk_bf16_f32 v210, v88, v89
	v_max_f32_e32 v90, 0, v90
	v_max_f32_e32 v91, 0, v91
	v_mul_f32_e32 v90, v90, v90
	v_mul_f32_e32 v91, v91, v91
	v_cvt_pk_bf16_f32 v211, v90, v91
	v_max_f32_e32 v92, 0, v92
	v_max_f32_e32 v93, 0, v93
	v_mul_f32_e32 v92, v92, v92
	v_mul_f32_e32 v93, v93, v93
	v_cvt_pk_bf16_f32 v212, v92, v93
	v_max_f32_e32 v94, 0, v94
	v_max_f32_e32 v95, 0, v95
	v_mul_f32_e32 v94, v94, v94
	v_mul_f32_e32 v95, v95, v95
	v_cvt_pk_bf16_f32 v213, v94, v95
	v_max_f32_e32 v64, 0, v64
	v_max_f32_e32 v65, 0, v65
	v_mul_f32_e32 v64, v64, v64
	v_mul_f32_e32 v65, v65, v65
	v_cvt_pk_bf16_f32 v214, v64, v65
	v_max_f32_e32 v66, 0, v66
	v_max_f32_e32 v67, 0, v67
	v_mul_f32_e32 v66, v66, v66
	v_mul_f32_e32 v67, v67, v67
	v_cvt_pk_bf16_f32 v215, v66, v67
	v_max_f32_e32 v68, 0, v68
	v_max_f32_e32 v69, 0, v69
	v_mul_f32_e32 v68, v68, v68
	v_mul_f32_e32 v69, v69, v69
	v_cvt_pk_bf16_f32 v216, v68, v69
	v_max_f32_e32 v70, 0, v70
	v_max_f32_e32 v71, 0, v71
	v_mul_f32_e32 v70, v70, v70
	v_mul_f32_e32 v71, v71, v71
	v_cvt_pk_bf16_f32 v217, v70, v71
	v_max_f32_e32 v72, 0, v72
	v_max_f32_e32 v73, 0, v73
	v_mul_f32_e32 v72, v72, v72
	v_mul_f32_e32 v73, v73, v73
	v_cvt_pk_bf16_f32 v218, v72, v73
	v_max_f32_e32 v74, 0, v74
	v_max_f32_e32 v75, 0, v75
	v_mul_f32_e32 v74, v74, v74
	v_mul_f32_e32 v75, v75, v75
	v_cvt_pk_bf16_f32 v219, v74, v75
	v_max_f32_e32 v76, 0, v76
	v_max_f32_e32 v77, 0, v77
	v_mul_f32_e32 v76, v76, v76
	v_mul_f32_e32 v77, v77, v77
	v_cvt_pk_bf16_f32 v220, v76, v77
	v_max_f32_e32 v78, 0, v78
	v_max_f32_e32 v79, 0, v79
	v_mul_f32_e32 v78, v78, v78
	v_mul_f32_e32 v79, v79, v79
	v_cvt_pk_bf16_f32 v221, v78, v79
	v_max_f32_e32 v48, 0, v48
	v_max_f32_e32 v49, 0, v49
	v_mul_f32_e32 v48, v48, v48
	v_mul_f32_e32 v49, v49, v49
	v_cvt_pk_bf16_f32 v222, v48, v49
	v_max_f32_e32 v50, 0, v50
	v_max_f32_e32 v51, 0, v51
	v_mul_f32_e32 v50, v50, v50
	v_mul_f32_e32 v51, v51, v51
	v_cvt_pk_bf16_f32 v223, v50, v51
	v_max_f32_e32 v52, 0, v52
	v_max_f32_e32 v53, 0, v53
	v_mul_f32_e32 v52, v52, v52
	v_mul_f32_e32 v53, v53, v53
	v_cvt_pk_bf16_f32 v224, v52, v53
	v_max_f32_e32 v54, 0, v54
	v_max_f32_e32 v55, 0, v55
	v_mul_f32_e32 v54, v54, v54
	v_mul_f32_e32 v55, v55, v55
	v_cvt_pk_bf16_f32 v225, v54, v55
	v_max_f32_e32 v56, 0, v56
	v_max_f32_e32 v57, 0, v57
	v_mul_f32_e32 v56, v56, v56
	v_mul_f32_e32 v57, v57, v57
	v_cvt_pk_bf16_f32 v226, v56, v57
	v_max_f32_e32 v58, 0, v58
	v_max_f32_e32 v59, 0, v59
	v_mul_f32_e32 v58, v58, v58
	v_mul_f32_e32 v59, v59, v59
	v_cvt_pk_bf16_f32 v227, v58, v59
	v_max_f32_e32 v60, 0, v60
	v_max_f32_e32 v61, 0, v61
	v_mul_f32_e32 v60, v60, v60
	v_mul_f32_e32 v61, v61, v61
	v_cvt_pk_bf16_f32 v228, v60, v61
	v_max_f32_e32 v62, 0, v62
	v_max_f32_e32 v63, 0, v63
	v_mul_f32_e32 v62, v62, v62
	v_mul_f32_e32 v63, v63, v63
	v_cvt_pk_bf16_f32 v229, v62, v63
	v_max_f32_e32 v32, 0, v32
	v_max_f32_e32 v33, 0, v33
	v_mul_f32_e32 v32, v32, v32
	v_mul_f32_e32 v33, v33, v33
	v_cvt_pk_bf16_f32 v230, v32, v33
	v_max_f32_e32 v34, 0, v34
	v_max_f32_e32 v35, 0, v35
	v_mul_f32_e32 v34, v34, v34
	v_mul_f32_e32 v35, v35, v35
	v_cvt_pk_bf16_f32 v231, v34, v35
	v_max_f32_e32 v36, 0, v36
	v_max_f32_e32 v37, 0, v37
	v_mul_f32_e32 v36, v36, v36
	v_mul_f32_e32 v37, v37, v37
	v_cvt_pk_bf16_f32 v232, v36, v37
	v_max_f32_e32 v38, 0, v38
	v_max_f32_e32 v39, 0, v39
	v_mul_f32_e32 v38, v38, v38
	v_mul_f32_e32 v39, v39, v39
	v_cvt_pk_bf16_f32 v233, v38, v39
	v_max_f32_e32 v40, 0, v40
	v_max_f32_e32 v41, 0, v41
	v_mul_f32_e32 v40, v40, v40
	v_mul_f32_e32 v41, v41, v41
	v_cvt_pk_bf16_f32 v234, v40, v41
	v_max_f32_e32 v42, 0, v42
	v_max_f32_e32 v43, 0, v43
	v_mul_f32_e32 v42, v42, v42
	v_mul_f32_e32 v43, v43, v43
	v_cvt_pk_bf16_f32 v235, v42, v43
	v_max_f32_e32 v44, 0, v44
	v_max_f32_e32 v45, 0, v45
	v_mul_f32_e32 v44, v44, v44
	v_mul_f32_e32 v45, v45, v45
	v_cvt_pk_bf16_f32 v236, v44, v45
	v_max_f32_e32 v46, 0, v46
	v_max_f32_e32 v47, 0, v47
	v_mul_f32_e32 v46, v46, v46
	v_mul_f32_e32 v47, v47, v47
	v_cvt_pk_bf16_f32 v237, v46, v47
	v_max_f32_e32 v16, 0, v16
	v_max_f32_e32 v17, 0, v17
	v_mul_f32_e32 v16, v16, v16
	v_mul_f32_e32 v17, v17, v17
	v_cvt_pk_bf16_f32 v238, v16, v17
	v_max_f32_e32 v18, 0, v18
	v_max_f32_e32 v19, 0, v19
	v_mul_f32_e32 v18, v18, v18
	v_mul_f32_e32 v19, v19, v19
	v_cvt_pk_bf16_f32 v239, v18, v19
	v_max_f32_e32 v20, 0, v20
	v_max_f32_e32 v21, 0, v21
	v_mul_f32_e32 v20, v20, v20
	v_mul_f32_e32 v21, v21, v21
	v_cvt_pk_bf16_f32 v240, v20, v21
	v_max_f32_e32 v22, 0, v22
	v_max_f32_e32 v23, 0, v23
	v_mul_f32_e32 v22, v22, v22
	v_mul_f32_e32 v23, v23, v23
	v_cvt_pk_bf16_f32 v241, v22, v23
	v_max_f32_e32 v24, 0, v24
	v_max_f32_e32 v25, 0, v25
	v_mul_f32_e32 v24, v24, v24
	v_mul_f32_e32 v25, v25, v25
	v_cvt_pk_bf16_f32 v242, v24, v25
	v_max_f32_e32 v26, 0, v26
	v_max_f32_e32 v27, 0, v27
	v_mul_f32_e32 v26, v26, v26
	v_mul_f32_e32 v27, v27, v27
	v_cvt_pk_bf16_f32 v243, v26, v27
	v_max_f32_e32 v28, 0, v28
	v_max_f32_e32 v29, 0, v29
	v_mul_f32_e32 v28, v28, v28
	v_mul_f32_e32 v29, v29, v29
	v_cvt_pk_bf16_f32 v244, v28, v29
	v_max_f32_e32 v30, 0, v30
	v_max_f32_e32 v31, 0, v31
	v_mul_f32_e32 v30, v30, v30
	v_mul_f32_e32 v31, v31, v31
	v_cvt_pk_bf16_f32 v245, v30, v31
	v_max_f32_e32 v0, 0, v0
	v_max_f32_e32 v1, 0, v1
	v_mul_f32_e32 v0, v0, v0
	v_mul_f32_e32 v1, v1, v1
	v_cvt_pk_bf16_f32 v246, v0, v1
	v_max_f32_e32 v2, 0, v2
	v_max_f32_e32 v3, 0, v3
	v_mul_f32_e32 v2, v2, v2
	v_mul_f32_e32 v3, v3, v3
	v_cvt_pk_bf16_f32 v247, v2, v3
	v_max_f32_e32 v4, 0, v4
	v_max_f32_e32 v5, 0, v5
	v_mul_f32_e32 v4, v4, v4
	v_mul_f32_e32 v5, v5, v5
	v_cvt_pk_bf16_f32 v248, v4, v5
	v_max_f32_e32 v6, 0, v6
	v_max_f32_e32 v7, 0, v7
	v_mul_f32_e32 v6, v6, v6
	v_mul_f32_e32 v7, v7, v7
	v_cvt_pk_bf16_f32 v249, v6, v7
	v_max_f32_e32 v8, 0, v8
	v_max_f32_e32 v9, 0, v9
	v_mul_f32_e32 v8, v8, v8
	v_mul_f32_e32 v9, v9, v9
	v_cvt_pk_bf16_f32 v250, v8, v9
	v_max_f32_e32 v10, 0, v10
	v_max_f32_e32 v11, 0, v11
	v_mul_f32_e32 v10, v10, v10
	v_mul_f32_e32 v11, v11, v11
	v_cvt_pk_bf16_f32 v251, v10, v11
	v_max_f32_e32 v12, 0, v12
	v_max_f32_e32 v13, 0, v13
	v_mul_f32_e32 v12, v12, v12
	v_mul_f32_e32 v13, v13, v13
	v_cvt_pk_bf16_f32 v252, v12, v13
	v_max_f32_e32 v14, 0, v14
	v_max_f32_e32 v15, 0, v15
	v_mul_f32_e32 v14, v14, v14
	v_mul_f32_e32 v15, v15, v15
	v_cvt_pk_bf16_f32 v253, v14, v15
	s_add_i32 s57, s57, s22
	s_add_i32 s56, s56, s22
	s_cmpk_lt_u32 s57, 0x240
	s_cbranch_scc1 .LBB0_996
	v_and_b32_e32 v3, 15, v182
	v_lshrrev_b32_e32 v4, 4, v182
	v_mul_u32_u24_e32 v2, 0x2000, v4
	v_lshl_add_u32 v2, v3, 4, v2
	v_mul_u32_u24_e32 v1, 0x110, v4
	v_lshl_add_u32 v1, v3, 4, v1
	v_lshrrev_b32_e32 v3, 7, v182
	v_bfe_u32 v4, v182, 5, 1
	v_lshlrev_b32_e32 v3, 6, v3
	v_lshl_or_b32 v3, v4, 2, v3
	v_mul_u32_u24_e32 v3, 136, v3
	v_and_b32_e32 v4, 0x5f, v182
	v_add_lshl_u32 v0, v3, v4, 1
	s_barrier
	ds_write_b16 v0, v190
	ds_write_b16_d16_hi v0, v190 offset:272
	ds_write_b16 v0, v191 offset:544
	ds_write_b16_d16_hi v0, v191 offset:816
	ds_write_b16 v0, v192 offset:2176
	ds_write_b16_d16_hi v0, v192 offset:2448
	ds_write_b16 v0, v193 offset:2720
	ds_write_b16_d16_hi v0, v193 offset:2992
	ds_write_b16 v0, v194 offset:4352
	ds_write_b16_d16_hi v0, v194 offset:4624
	ds_write_b16 v0, v195 offset:4896
	ds_write_b16_d16_hi v0, v195 offset:5168
	ds_write_b16 v0, v196 offset:6528
	ds_write_b16_d16_hi v0, v196 offset:6800
	ds_write_b16 v0, v197 offset:7072
	ds_write_b16_d16_hi v0, v197 offset:7344
	ds_write_b16 v0, v198 offset:64
	ds_write_b16_d16_hi v0, v198 offset:336
	ds_write_b16 v0, v199 offset:608
	ds_write_b16_d16_hi v0, v199 offset:880
	ds_write_b16 v0, v200 offset:2240
	ds_write_b16_d16_hi v0, v200 offset:2512
	ds_write_b16 v0, v201 offset:2784
	ds_write_b16_d16_hi v0, v201 offset:3056
	ds_write_b16 v0, v202 offset:4416
	ds_write_b16_d16_hi v0, v202 offset:4688
	ds_write_b16 v0, v203 offset:4960
	ds_write_b16_d16_hi v0, v203 offset:5232
	ds_write_b16 v0, v204 offset:6592
	ds_write_b16_d16_hi v0, v204 offset:6864
	ds_write_b16 v0, v205 offset:7136
	ds_write_b16_d16_hi v0, v205 offset:7408
	ds_write_b16 v0, v206 offset:8704
	ds_write_b16_d16_hi v0, v206 offset:8976
	ds_write_b16 v0, v207 offset:9248
	ds_write_b16_d16_hi v0, v207 offset:9520
	ds_write_b16 v0, v208 offset:10880
	ds_write_b16_d16_hi v0, v208 offset:11152
	ds_write_b16 v0, v209 offset:11424
	ds_write_b16_d16_hi v0, v209 offset:11696
	ds_write_b16 v0, v210 offset:13056
	ds_write_b16_d16_hi v0, v210 offset:13328
	ds_write_b16 v0, v211 offset:13600
	ds_write_b16_d16_hi v0, v211 offset:13872
	ds_write_b16 v0, v212 offset:15232
	ds_write_b16_d16_hi v0, v212 offset:15504
	ds_write_b16 v0, v213 offset:15776
	ds_write_b16_d16_hi v0, v213 offset:16048
	ds_write_b16 v0, v214 offset:8768
	ds_write_b16_d16_hi v0, v214 offset:9040
	ds_write_b16 v0, v215 offset:9312
	ds_write_b16_d16_hi v0, v215 offset:9584
	ds_write_b16 v0, v216 offset:10944
	ds_write_b16_d16_hi v0, v216 offset:11216
	ds_write_b16 v0, v217 offset:11488
	ds_write_b16_d16_hi v0, v217 offset:11760
	ds_write_b16 v0, v218 offset:13120
	ds_write_b16_d16_hi v0, v218 offset:13392
	ds_write_b16 v0, v219 offset:13664
	ds_write_b16_d16_hi v0, v219 offset:13936
	ds_write_b16 v0, v220 offset:15296
	ds_write_b16_d16_hi v0, v220 offset:15568
	ds_write_b16 v0, v221 offset:15840
	ds_write_b16_d16_hi v0, v221 offset:16112
	s_waitcnt lgkmcnt(0)
	s_barrier
	ds_read_b128 v[8:11], v1
	ds_read_b128 v[12:15], v1 offset:4352
	ds_read_b128 v[16:19], v1 offset:8704
	ds_read_b128 v[20:23], v1 offset:13056
	ds_read_b128 v[24:27], v1 offset:17408
	ds_read_b128 v[28:31], v1 offset:21760
	ds_read_b128 v[32:35], v1 offset:26112
	ds_read_b128 v[36:39], v1 offset:30464
	s_add_u32 s38, s44, 0x0
	s_addc_u32 s39, s45, 0
	s_waitcnt lgkmcnt(7)
	global_store_dwordx4 v2, v[8:11], s[38:39]
	s_add_u32 s38, s44, 0x20000
	s_addc_u32 s39, s45, 0
	s_waitcnt lgkmcnt(6)
	global_store_dwordx4 v2, v[12:15], s[38:39]
	s_add_u32 s38, s44, 0x40000
	s_addc_u32 s39, s45, 0
	s_waitcnt lgkmcnt(5)
	global_store_dwordx4 v2, v[16:19], s[38:39]
	s_add_u32 s38, s44, 0x60000
	s_addc_u32 s39, s45, 0
	s_waitcnt lgkmcnt(4)
	global_store_dwordx4 v2, v[20:23], s[38:39]
	s_add_u32 s38, s44, 0x100000
	s_addc_u32 s39, s45, 0
	s_waitcnt lgkmcnt(3)
	global_store_dwordx4 v2, v[24:27], s[38:39]
	s_add_u32 s38, s44, 0x120000
	s_addc_u32 s39, s45, 0
	s_waitcnt lgkmcnt(2)
	global_store_dwordx4 v2, v[28:31], s[38:39]
	s_add_u32 s38, s44, 0x140000
	s_addc_u32 s39, s45, 0
	s_waitcnt lgkmcnt(1)
	global_store_dwordx4 v2, v[32:35], s[38:39]
	s_add_u32 s38, s44, 0x160000
	s_addc_u32 s39, s45, 0
	s_waitcnt lgkmcnt(0)
	global_store_dwordx4 v2, v[36:39], s[38:39]
	s_barrier
	ds_write_b16 v0, v222
	ds_write_b16_d16_hi v0, v222 offset:272
	ds_write_b16 v0, v223 offset:544
	ds_write_b16_d16_hi v0, v223 offset:816
	ds_write_b16 v0, v224 offset:2176
	ds_write_b16_d16_hi v0, v224 offset:2448
	ds_write_b16 v0, v225 offset:2720
	ds_write_b16_d16_hi v0, v225 offset:2992
	ds_write_b16 v0, v226 offset:4352
	ds_write_b16_d16_hi v0, v226 offset:4624
	ds_write_b16 v0, v227 offset:4896
	ds_write_b16_d16_hi v0, v227 offset:5168
	ds_write_b16 v0, v228 offset:6528
	ds_write_b16_d16_hi v0, v228 offset:6800
	ds_write_b16 v0, v229 offset:7072
	ds_write_b16_d16_hi v0, v229 offset:7344
	ds_write_b16 v0, v230 offset:64
	ds_write_b16_d16_hi v0, v230 offset:336
	ds_write_b16 v0, v231 offset:608
	ds_write_b16_d16_hi v0, v231 offset:880
	ds_write_b16 v0, v232 offset:2240
	ds_write_b16_d16_hi v0, v232 offset:2512
	ds_write_b16 v0, v233 offset:2784
	ds_write_b16_d16_hi v0, v233 offset:3056
	ds_write_b16 v0, v234 offset:4416
	ds_write_b16_d16_hi v0, v234 offset:4688
	ds_write_b16 v0, v235 offset:4960
	ds_write_b16_d16_hi v0, v235 offset:5232
	ds_write_b16 v0, v236 offset:6592
	ds_write_b16_d16_hi v0, v236 offset:6864
	ds_write_b16 v0, v237 offset:7136
	ds_write_b16_d16_hi v0, v237 offset:7408
	ds_write_b16 v0, v238 offset:8704
	ds_write_b16_d16_hi v0, v238 offset:8976
	ds_write_b16 v0, v239 offset:9248
	ds_write_b16_d16_hi v0, v239 offset:9520
	ds_write_b16 v0, v240 offset:10880
	ds_write_b16_d16_hi v0, v240 offset:11152
	ds_write_b16 v0, v241 offset:11424
	ds_write_b16_d16_hi v0, v241 offset:11696
	ds_write_b16 v0, v242 offset:13056
	ds_write_b16_d16_hi v0, v242 offset:13328
	ds_write_b16 v0, v243 offset:13600
	ds_write_b16_d16_hi v0, v243 offset:13872
	ds_write_b16 v0, v244 offset:15232
	ds_write_b16_d16_hi v0, v244 offset:15504
	ds_write_b16 v0, v245 offset:15776
	ds_write_b16_d16_hi v0, v245 offset:16048
	ds_write_b16 v0, v246 offset:8768
	ds_write_b16_d16_hi v0, v246 offset:9040
	ds_write_b16 v0, v247 offset:9312
	ds_write_b16_d16_hi v0, v247 offset:9584
	ds_write_b16 v0, v248 offset:10944
	ds_write_b16_d16_hi v0, v248 offset:11216
	ds_write_b16 v0, v249 offset:11488
	ds_write_b16_d16_hi v0, v249 offset:11760
	ds_write_b16 v0, v250 offset:13120
	ds_write_b16_d16_hi v0, v250 offset:13392
	ds_write_b16 v0, v251 offset:13664
	ds_write_b16_d16_hi v0, v251 offset:13936
	ds_write_b16 v0, v252 offset:15296
	ds_write_b16_d16_hi v0, v252 offset:15568
	ds_write_b16 v0, v253 offset:15840
	ds_write_b16_d16_hi v0, v253 offset:16112
	s_waitcnt lgkmcnt(0)
	s_barrier
	ds_read_b128 v[8:11], v1
	ds_read_b128 v[12:15], v1 offset:4352
	ds_read_b128 v[16:19], v1 offset:8704
	ds_read_b128 v[20:23], v1 offset:13056
	ds_read_b128 v[24:27], v1 offset:17408
	ds_read_b128 v[28:31], v1 offset:21760
	ds_read_b128 v[32:35], v1 offset:26112
	ds_read_b128 v[36:39], v1 offset:30464
	s_add_u32 s38, s44, 0x80000
	s_addc_u32 s39, s45, 0
	s_waitcnt lgkmcnt(7)
	global_store_dwordx4 v2, v[8:11], s[38:39]
	s_add_u32 s38, s44, 0xa0000
	s_addc_u32 s39, s45, 0
	s_waitcnt lgkmcnt(6)
	global_store_dwordx4 v2, v[12:15], s[38:39]
	s_add_u32 s38, s44, 0xc0000
	s_addc_u32 s39, s45, 0
	s_waitcnt lgkmcnt(5)
	global_store_dwordx4 v2, v[16:19], s[38:39]
	s_add_u32 s38, s44, 0xe0000
	s_addc_u32 s39, s45, 0
	s_waitcnt lgkmcnt(4)
	global_store_dwordx4 v2, v[20:23], s[38:39]
	s_add_u32 s38, s44, 0x180000
	s_addc_u32 s39, s45, 0
	s_waitcnt lgkmcnt(3)
	global_store_dwordx4 v2, v[24:27], s[38:39]
	s_add_u32 s38, s44, 0x1a0000
	s_addc_u32 s39, s45, 0
	s_waitcnt lgkmcnt(2)
	global_store_dwordx4 v2, v[28:31], s[38:39]
	s_add_u32 s38, s44, 0x1c0000
	s_addc_u32 s39, s45, 0
	s_waitcnt lgkmcnt(1)
	global_store_dwordx4 v2, v[32:35], s[38:39]
	s_add_u32 s38, s44, 0x1e0000
	s_addc_u32 s39, s45, 0
	s_waitcnt lgkmcnt(0)
	global_store_dwordx4 v2, v[36:39], s[38:39]
	s_mov_b32 s43, 0
	s_branch .LBB0_989

.LBB0_1284:
	ds_read_b128 v[216:219], v176 offset:36864
	ds_read_b128 v[200:203], v188
	ds_read_b128 v[220:223], v176 offset:41472
	ds_read_b128 v[204:207], v188 offset:4608
	ds_read_b128 v[208:211], v188 offset:9216
	ds_read_b128 v[212:215], v187
	s_waitcnt lgkmcnt(4)
	v_mfma_f32_32x32x16_bf16 v[112:127], v[200:203], v[216:219], v[112:127]
	ds_read_b128 v[240:243], v176 offset:36896
	global_load_dwordx4 v[140:143], v190, s[44:45]
	s_waitcnt lgkmcnt(4)
	v_mfma_f32_32x32x16_bf16 v[96:111], v[200:203], v[220:223], v[96:111]
	ds_read_b128 v[224:227], v188 offset:32
	global_load_dwordx4 v[160:163], v191, s[44:45]
	s_waitcnt lgkmcnt(4)
	v_mfma_f32_32x32x16_bf16 v[80:95], v[204:207], v[216:219], v[80:95]
	ds_read_b128 v[244:247], v176 offset:41504
	global_load_dwordx4 v[168:171], v192, s[44:45]
	s_waitcnt lgkmcnt(5)
	v_mfma_f32_32x32x16_bf16 v[64:79], v[204:207], v[220:223], v[64:79]
	ds_read_b128 v[228:231], v188 offset:4640
	global_load_dwordx4 v[172:175], v193, s[44:45]
	s_waitcnt lgkmcnt(5)
	v_mfma_f32_32x32x16_bf16 v[48:63], v[208:211], v[216:219], v[48:63]
	ds_read_b128 v[232:235], v188 offset:9248
	global_load_dwordx4 v[164:167], v190, s[42:43]
	s_waitcnt lgkmcnt(6)
	v_mfma_f32_32x32x16_bf16 v[32:47], v[208:211], v[220:223], v[32:47]
	ds_read_b128 v[236:239], v187 offset:32
	global_load_dwordx4 v[128:131], v191, s[42:43]
	s_waitcnt lgkmcnt(6)
	v_mfma_f32_32x32x16_bf16 v[16:31], v[212:215], v[216:219], v[16:31]
	global_load_dwordx4 v[132:135], v192, s[42:43]
	s_waitcnt lgkmcnt(6)
	v_mfma_f32_32x32x16_bf16 v[0:15], v[212:215], v[220:223], v[0:15]
	global_load_dwordx4 v[136:139], v193, s[42:43]
	s_waitcnt lgkmcnt(4)
	v_mfma_f32_32x32x16_bf16 v[112:127], v[224:227], v[240:243], v[112:127]
	ds_read_b128 v[200:203], v188 offset:64
	global_load_dwordx4 v[144:147], v194, s[42:43]
	s_waitcnt lgkmcnt(4)
	v_mfma_f32_32x32x16_bf16 v[96:111], v[224:227], v[244:247], v[96:111]
	ds_read_b128 v[204:207], v188 offset:4672
	global_load_dwordx4 v[148:151], v195, s[42:43]
	s_waitcnt lgkmcnt(4)
	v_mfma_f32_32x32x16_bf16 v[80:95], v[228:231], v[240:243], v[80:95]
	ds_read_b128 v[208:211], v188 offset:9280
	global_load_dwordx4 v[152:155], v196, s[42:43]
	s_waitcnt lgkmcnt(5)
	v_mfma_f32_32x32x16_bf16 v[64:79], v[228:231], v[244:247], v[64:79]
	ds_read_b128 v[212:215], v187 offset:64
	global_load_dwordx4 v[156:159], v197, s[42:43]
	s_add_u32 s42, s42, 0x80
	s_addc_u32 s43, s43, 0
	s_add_u32 s44, s44, 0x80
	s_addc_u32 s45, s45, 0
	s_add_u32 s16, s16, 0x80
	s_waitcnt lgkmcnt(5)
	v_mfma_f32_32x32x16_bf16 v[48:63], v[232:235], v[240:243], v[48:63]
	ds_read_b128 v[216:219], v176 offset:36928
	s_waitcnt lgkmcnt(6)
	v_mfma_f32_32x32x16_bf16 v[32:47], v[232:235], v[244:247], v[32:47]
	ds_read_b128 v[220:223], v176 offset:41536
	s_waitcnt lgkmcnt(6)
	v_mfma_f32_32x32x16_bf16 v[16:31], v[236:239], v[240:243], v[16:31]
	s_waitcnt lgkmcnt(6)
	v_mfma_f32_32x32x16_bf16 v[0:15], v[236:239], v[244:247], v[0:15]
	s_waitcnt lgkmcnt(1)
	v_mfma_f32_32x32x16_bf16 v[112:127], v[200:203], v[216:219], v[112:127]
	ds_read_b128 v[224:227], v188 offset:96
	s_waitcnt lgkmcnt(1)
	v_mfma_f32_32x32x16_bf16 v[96:111], v[200:203], v[220:223], v[96:111]
	ds_read_b128 v[228:231], v188 offset:4704
	s_waitcnt lgkmcnt(3)
	v_mfma_f32_32x32x16_bf16 v[80:95], v[204:207], v[216:219], v[80:95]
	ds_read_b128 v[232:235], v188 offset:9312
	s_waitcnt lgkmcnt(3)
	v_mfma_f32_32x32x16_bf16 v[64:79], v[204:207], v[220:223], v[64:79]
	ds_read_b128 v[236:239], v187 offset:96
	s_waitcnt lgkmcnt(5)
	v_mfma_f32_32x32x16_bf16 v[48:63], v[208:211], v[216:219], v[48:63]
	ds_read_b128 v[240:243], v176 offset:36960
	s_waitcnt lgkmcnt(5)
	v_mfma_f32_32x32x16_bf16 v[32:47], v[208:211], v[220:223], v[32:47]
	ds_read_b128 v[244:247], v176 offset:41568
	s_waitcnt lgkmcnt(7)
	v_mfma_f32_32x32x16_bf16 v[16:31], v[212:215], v[216:219], v[16:31]
	s_waitcnt lgkmcnt(6)
	v_mfma_f32_32x32x16_bf16 v[0:15], v[212:215], v[220:223], v[0:15]
	s_waitcnt lgkmcnt(0)
	s_barrier
	s_waitcnt vmcnt(0)
	s_waitcnt lgkmcnt(1)
	v_mfma_f32_32x32x16_bf16 v[112:127], v[224:227], v[240:243], v[112:127]
	ds_write_b128 v189, v[164:167]
	ds_write_b128 v189, v[128:131] offset:4608
	s_waitcnt lgkmcnt(2)
	v_mfma_f32_32x32x16_bf16 v[96:111], v[224:227], v[244:247], v[96:111]
	ds_write_b128 v189, v[132:135] offset:9216
	s_waitcnt lgkmcnt(4)
	v_mfma_f32_32x32x16_bf16 v[80:95], v[228:231], v[240:243], v[80:95]
	ds_write_b128 v189, v[136:139] offset:13824
	ds_write_b128 v189, v[144:147] offset:18432
	s_waitcnt lgkmcnt(5)
	v_mfma_f32_32x32x16_bf16 v[64:79], v[228:231], v[244:247], v[64:79]
	ds_write_b128 v189, v[148:151] offset:23040
	s_waitcnt lgkmcnt(7)
	v_mfma_f32_32x32x16_bf16 v[48:63], v[232:235], v[240:243], v[48:63]
	ds_write_b128 v189, v[152:155] offset:27648
	ds_write_b128 v189, v[156:159] offset:32256
	s_waitcnt lgkmcnt(8)
	v_mfma_f32_32x32x16_bf16 v[32:47], v[232:235], v[244:247], v[32:47]
	ds_write_b128 v189, v[140:143] offset:36864
	s_waitcnt lgkmcnt(10)
	v_mfma_f32_32x32x16_bf16 v[16:31], v[236:239], v[240:243], v[16:31]
	ds_write_b128 v189, v[160:163] offset:41472
	ds_write_b128 v189, v[168:171] offset:46080
	s_waitcnt lgkmcnt(11)
	v_mfma_f32_32x32x16_bf16 v[0:15], v[236:239], v[244:247], v[0:15]
	ds_write_b128 v189, v[172:175] offset:50688
	s_waitcnt lgkmcnt(0)
	s_barrier
	s_cmpk_lg_i32 s16, 0x780
	s_cbranch_scc1 .LBB0_1284
	ds_read_b128 v[216:219], v176 offset:36864
	ds_read_b128 v[200:203], v188
	ds_read_b128 v[220:223], v176 offset:41472
	ds_read_b128 v[204:207], v188 offset:4608
	ds_read_b128 v[208:211], v188 offset:9216
	ds_read_b128 v[212:215], v187
	s_waitcnt lgkmcnt(4)
	v_mfma_f32_32x32x16_bf16 v[112:127], v[200:203], v[216:219], v[112:127]
	ds_read_b128 v[240:243], v176 offset:36896
	s_waitcnt lgkmcnt(4)
	v_mfma_f32_32x32x16_bf16 v[96:111], v[200:203], v[220:223], v[96:111]
	ds_read_b128 v[224:227], v188 offset:32
	s_waitcnt lgkmcnt(4)
	v_mfma_f32_32x32x16_bf16 v[80:95], v[204:207], v[216:219], v[80:95]
	ds_read_b128 v[244:247], v176 offset:41504
	s_waitcnt lgkmcnt(5)
	v_mfma_f32_32x32x16_bf16 v[64:79], v[204:207], v[220:223], v[64:79]
	ds_read_b128 v[228:231], v188 offset:4640
	s_waitcnt lgkmcnt(5)
	v_mfma_f32_32x32x16_bf16 v[48:63], v[208:211], v[216:219], v[48:63]
	ds_read_b128 v[232:235], v188 offset:9248
	s_waitcnt lgkmcnt(6)
	v_mfma_f32_32x32x16_bf16 v[32:47], v[208:211], v[220:223], v[32:47]
	ds_read_b128 v[236:239], v187 offset:32
	s_waitcnt lgkmcnt(6)
	v_mfma_f32_32x32x16_bf16 v[16:31], v[212:215], v[216:219], v[16:31]
	s_waitcnt lgkmcnt(6)
	v_mfma_f32_32x32x16_bf16 v[0:15], v[212:215], v[220:223], v[0:15]
	s_waitcnt lgkmcnt(4)
	v_mfma_f32_32x32x16_bf16 v[112:127], v[224:227], v[240:243], v[112:127]
	ds_read_b128 v[200:203], v188 offset:64
	s_waitcnt lgkmcnt(4)
	v_mfma_f32_32x32x16_bf16 v[96:111], v[224:227], v[244:247], v[96:111]
	ds_read_b128 v[204:207], v188 offset:4672
	s_waitcnt lgkmcnt(4)
	v_mfma_f32_32x32x16_bf16 v[80:95], v[228:231], v[240:243], v[80:95]
	ds_read_b128 v[208:211], v188 offset:9280
	s_waitcnt lgkmcnt(5)
	v_mfma_f32_32x32x16_bf16 v[64:79], v[228:231], v[244:247], v[64:79]
	ds_read_b128 v[212:215], v187 offset:64
	s_waitcnt lgkmcnt(5)
	v_mfma_f32_32x32x16_bf16 v[48:63], v[232:235], v[240:243], v[48:63]
	ds_read_b128 v[216:219], v176 offset:36928
	s_waitcnt lgkmcnt(6)
	v_mfma_f32_32x32x16_bf16 v[32:47], v[232:235], v[244:247], v[32:47]
	ds_read_b128 v[220:223], v176 offset:41536
	s_waitcnt lgkmcnt(6)
	v_mfma_f32_32x32x16_bf16 v[16:31], v[236:239], v[240:243], v[16:31]
	s_waitcnt lgkmcnt(6)
	v_mfma_f32_32x32x16_bf16 v[0:15], v[236:239], v[244:247], v[0:15]
	s_waitcnt lgkmcnt(1)
	v_mfma_f32_32x32x16_bf16 v[112:127], v[200:203], v[216:219], v[112:127]
	ds_read_b128 v[224:227], v188 offset:96
	s_waitcnt lgkmcnt(1)
	v_mfma_f32_32x32x16_bf16 v[96:111], v[200:203], v[220:223], v[96:111]
	ds_read_b128 v[228:231], v188 offset:4704
	s_waitcnt lgkmcnt(3)
	v_mfma_f32_32x32x16_bf16 v[80:95], v[204:207], v[216:219], v[80:95]
	ds_read_b128 v[232:235], v188 offset:9312
	s_waitcnt lgkmcnt(3)
	v_mfma_f32_32x32x16_bf16 v[64:79], v[204:207], v[220:223], v[64:79]
	ds_read_b128 v[236:239], v187 offset:96
	s_waitcnt lgkmcnt(5)
	v_mfma_f32_32x32x16_bf16 v[48:63], v[208:211], v[216:219], v[48:63]
	ds_read_b128 v[240:243], v176 offset:36960
	s_waitcnt lgkmcnt(5)
	v_mfma_f32_32x32x16_bf16 v[32:47], v[208:211], v[220:223], v[32:47]
	ds_read_b128 v[244:247], v176 offset:41568
	s_waitcnt lgkmcnt(7)
	v_mfma_f32_32x32x16_bf16 v[16:31], v[212:215], v[216:219], v[16:31]
	s_waitcnt lgkmcnt(6)
	v_mfma_f32_32x32x16_bf16 v[0:15], v[212:215], v[220:223], v[0:15]
	s_waitcnt lgkmcnt(1)
	v_mfma_f32_32x32x16_bf16 v[112:127], v[224:227], v[240:243], v[112:127]
	s_waitcnt lgkmcnt(0)
	v_mfma_f32_32x32x16_bf16 v[96:111], v[224:227], v[244:247], v[96:111]
	s_waitcnt lgkmcnt(1)
	v_mfma_f32_32x32x16_bf16 v[80:95], v[228:231], v[240:243], v[80:95]
	s_waitcnt lgkmcnt(0)
	v_mfma_f32_32x32x16_bf16 v[64:79], v[228:231], v[244:247], v[64:79]
	s_waitcnt lgkmcnt(1)
	v_mfma_f32_32x32x16_bf16 v[48:63], v[232:235], v[240:243], v[48:63]
	s_waitcnt lgkmcnt(0)
	v_mfma_f32_32x32x16_bf16 v[32:47], v[232:235], v[244:247], v[32:47]
	s_waitcnt lgkmcnt(1)
	v_mfma_f32_32x32x16_bf16 v[16:31], v[236:239], v[240:243], v[16:31]
	s_waitcnt lgkmcnt(0)
	v_mfma_f32_32x32x16_bf16 v[0:15], v[236:239], v[244:247], v[0:15]
	s_mul_i32 s41, s12, 0x1240
	s_add_u32 s42, s30, s41
	s_addc_u32 s43, s31, 0
	s_lshl_b32 s41, s8, 1
	s_add_u32 s42, s42, s41
	s_addc_u32 s43, s43, 0
	s_add_u32 s42, s42, 0x7157900
	s_addc_u32 s43, s43, 0
	v_and_b32_e32 v131, 15, v182
	v_lshrrev_b32_e32 v172, 4, v182
	v_lshl_add_u32 v130, v131, 3, s8
	s_movk_i32 s41, 0x920
	v_cmp_gt_u32_e64 s[44:45], s41, v130
	v_mul_u32_u24_e32 v164, 0x1240, v172
	v_lshl_add_u32 v164, v131, 4, v164
	v_add_u32_e32 v165, 0x12400, v164
	v_add_u32_e32 v166, 0x24800, v164
	v_add_u32_e32 v167, 0x36c00, v164
	v_add_u32_e32 v168, 0x92000, v164
	v_add_u32_e32 v169, 0xa4400, v164
	v_add_u32_e32 v170, 0xb6800, v164
	v_add_u32_e32 v171, 0xc8c00, v164
	v_mul_u32_u24_e32 v129, 0x110, v172
	v_lshl_add_u32 v129, v131, 4, v129
	v_lshrrev_b32_e32 v131, 7, v182
	v_bfe_u32 v172, v182, 5, 1
	v_lshlrev_b32_e32 v131, 6, v131
	v_lshl_or_b32 v131, v172, 2, v131
	v_mul_u32_u24_e32 v131, 136, v131
	v_and_b32_e32 v172, 0x5f, v182
	v_add_lshl_u32 v128, v131, v172, 1
	s_barrier
	v_cvt_pk_bf16_f32 v112, v112, v113
	v_cvt_pk_bf16_f32 v114, v114, v115
	v_cvt_pk_bf16_f32 v116, v116, v117
	v_cvt_pk_bf16_f32 v118, v118, v119
	v_cvt_pk_bf16_f32 v120, v120, v121
	v_cvt_pk_bf16_f32 v122, v122, v123
	v_cvt_pk_bf16_f32 v124, v124, v125
	v_cvt_pk_bf16_f32 v126, v126, v127
	v_cvt_pk_bf16_f32 v96, v96, v97
	v_cvt_pk_bf16_f32 v98, v98, v99
	v_cvt_pk_bf16_f32 v100, v100, v101
	v_cvt_pk_bf16_f32 v102, v102, v103
	v_cvt_pk_bf16_f32 v104, v104, v105
	v_cvt_pk_bf16_f32 v106, v106, v107
	v_cvt_pk_bf16_f32 v108, v108, v109
	v_cvt_pk_bf16_f32 v110, v110, v111
	v_cvt_pk_bf16_f32 v80, v80, v81
	v_cvt_pk_bf16_f32 v82, v82, v83
	v_cvt_pk_bf16_f32 v84, v84, v85
	v_cvt_pk_bf16_f32 v86, v86, v87
	v_cvt_pk_bf16_f32 v88, v88, v89
	v_cvt_pk_bf16_f32 v90, v90, v91
	v_cvt_pk_bf16_f32 v92, v92, v93
	v_cvt_pk_bf16_f32 v94, v94, v95
	v_cvt_pk_bf16_f32 v64, v64, v65
	v_cvt_pk_bf16_f32 v66, v66, v67
	v_cvt_pk_bf16_f32 v68, v68, v69
	v_cvt_pk_bf16_f32 v70, v70, v71
	v_cvt_pk_bf16_f32 v72, v72, v73
	v_cvt_pk_bf16_f32 v74, v74, v75
	v_cvt_pk_bf16_f32 v76, v76, v77
	v_cvt_pk_bf16_f32 v78, v78, v79
	ds_write_b16 v128, v112
	ds_write_b16_d16_hi v128, v112 offset:272
	ds_write_b16 v128, v114 offset:544
	ds_write_b16_d16_hi v128, v114 offset:816
	ds_write_b16 v128, v116 offset:2176
	ds_write_b16_d16_hi v128, v116 offset:2448
	ds_write_b16 v128, v118 offset:2720
	ds_write_b16_d16_hi v128, v118 offset:2992
	ds_write_b16 v128, v120 offset:4352
	ds_write_b16_d16_hi v128, v120 offset:4624
	ds_write_b16 v128, v122 offset:4896
	ds_write_b16_d16_hi v128, v122 offset:5168
	ds_write_b16 v128, v124 offset:6528
	ds_write_b16_d16_hi v128, v124 offset:6800
	ds_write_b16 v128, v126 offset:7072
	ds_write_b16_d16_hi v128, v126 offset:7344
	ds_write_b16 v128, v96 offset:64
	ds_write_b16_d16_hi v128, v96 offset:336
	ds_write_b16 v128, v98 offset:608
	ds_write_b16_d16_hi v128, v98 offset:880
	ds_write_b16 v128, v100 offset:2240
	ds_write_b16_d16_hi v128, v100 offset:2512
	ds_write_b16 v128, v102 offset:2784
	ds_write_b16_d16_hi v128, v102 offset:3056
	ds_write_b16 v128, v104 offset:4416
	ds_write_b16_d16_hi v128, v104 offset:4688
	ds_write_b16 v128, v106 offset:4960
	ds_write_b16_d16_hi v128, v106 offset:5232
	ds_write_b16 v128, v108 offset:6592
	ds_write_b16_d16_hi v128, v108 offset:6864
	ds_write_b16 v128, v110 offset:7136
	ds_write_b16_d16_hi v128, v110 offset:7408
	ds_write_b16 v128, v80 offset:8704
	ds_write_b16_d16_hi v128, v80 offset:8976
	ds_write_b16 v128, v82 offset:9248
	ds_write_b16_d16_hi v128, v82 offset:9520
	ds_write_b16 v128, v84 offset:10880
	ds_write_b16_d16_hi v128, v84 offset:11152
	ds_write_b16 v128, v86 offset:11424
	ds_write_b16_d16_hi v128, v86 offset:11696
	ds_write_b16 v128, v88 offset:13056
	ds_write_b16_d16_hi v128, v88 offset:13328
	ds_write_b16 v128, v90 offset:13600
	ds_write_b16_d16_hi v128, v90 offset:13872
	ds_write_b16 v128, v92 offset:15232
	ds_write_b16_d16_hi v128, v92 offset:15504
	ds_write_b16 v128, v94 offset:15776
	ds_write_b16_d16_hi v128, v94 offset:16048
	ds_write_b16 v128, v64 offset:8768
	ds_write_b16_d16_hi v128, v64 offset:9040
	ds_write_b16 v128, v66 offset:9312
	ds_write_b16_d16_hi v128, v66 offset:9584
	ds_write_b16 v128, v68 offset:10944
	ds_write_b16_d16_hi v128, v68 offset:11216
	ds_write_b16 v128, v70 offset:11488
	ds_write_b16_d16_hi v128, v70 offset:11760
	ds_write_b16 v128, v72 offset:13120
	ds_write_b16_d16_hi v128, v72 offset:13392
	ds_write_b16 v128, v74 offset:13664
	ds_write_b16_d16_hi v128, v74 offset:13936
	ds_write_b16 v128, v76 offset:15296
	ds_write_b16_d16_hi v128, v76 offset:15568
	ds_write_b16 v128, v78 offset:15840
	ds_write_b16_d16_hi v128, v78 offset:16112
	s_waitcnt lgkmcnt(0)
	s_barrier
	ds_read_b128 v[132:135], v129
	ds_read_b128 v[136:139], v129 offset:4352
	ds_read_b128 v[140:143], v129 offset:8704
	ds_read_b128 v[144:147], v129 offset:13056
	ds_read_b128 v[148:151], v129 offset:17408
	ds_read_b128 v[152:155], v129 offset:21760
	ds_read_b128 v[156:159], v129 offset:26112
	ds_read_b128 v[160:163], v129 offset:30464
	v_cvt_pk_bf16_f32 v48, v48, v49
	v_cvt_pk_bf16_f32 v50, v50, v51
	v_cvt_pk_bf16_f32 v52, v52, v53
	v_cvt_pk_bf16_f32 v54, v54, v55
	v_cvt_pk_bf16_f32 v56, v56, v57
	v_cvt_pk_bf16_f32 v58, v58, v59
	v_cvt_pk_bf16_f32 v60, v60, v61
	v_cvt_pk_bf16_f32 v62, v62, v63
	v_cvt_pk_bf16_f32 v32, v32, v33
	v_cvt_pk_bf16_f32 v34, v34, v35
	v_cvt_pk_bf16_f32 v36, v36, v37
	v_cvt_pk_bf16_f32 v38, v38, v39
	v_cvt_pk_bf16_f32 v40, v40, v41
	v_cvt_pk_bf16_f32 v42, v42, v43
	v_cvt_pk_bf16_f32 v44, v44, v45
	v_cvt_pk_bf16_f32 v46, v46, v47
	v_cvt_pk_bf16_f32 v16, v16, v17
	v_cvt_pk_bf16_f32 v18, v18, v19
	v_cvt_pk_bf16_f32 v20, v20, v21
	v_cvt_pk_bf16_f32 v22, v22, v23
	v_cvt_pk_bf16_f32 v24, v24, v25
	v_cvt_pk_bf16_f32 v26, v26, v27
	v_cvt_pk_bf16_f32 v28, v28, v29
	v_cvt_pk_bf16_f32 v30, v30, v31
	v_cvt_pk_bf16_f32 v0, v0, v1
	v_cvt_pk_bf16_f32 v2, v2, v3
	v_cvt_pk_bf16_f32 v4, v4, v5
	v_cvt_pk_bf16_f32 v6, v6, v7
	v_cvt_pk_bf16_f32 v8, v8, v9
	v_cvt_pk_bf16_f32 v10, v10, v11
	v_cvt_pk_bf16_f32 v12, v12, v13
	v_cvt_pk_bf16_f32 v14, v14, v15
	s_and_saveexec_b64 s[46:47], s[44:45]
	s_waitcnt lgkmcnt(7)
	global_store_dwordx4 v164, v[132:135], s[42:43]
	s_waitcnt lgkmcnt(6)
	global_store_dwordx4 v165, v[136:139], s[42:43]
	s_waitcnt lgkmcnt(5)
	global_store_dwordx4 v166, v[140:143], s[42:43]
	s_waitcnt lgkmcnt(4)
	global_store_dwordx4 v167, v[144:147], s[42:43]
	s_waitcnt lgkmcnt(3)
	global_store_dwordx4 v168, v[148:151], s[42:43]
	s_waitcnt lgkmcnt(2)
	global_store_dwordx4 v169, v[152:155], s[42:43]
	s_waitcnt lgkmcnt(1)
	global_store_dwordx4 v170, v[156:159], s[42:43]
	s_waitcnt lgkmcnt(0)
	global_store_dwordx4 v171, v[160:163], s[42:43]
	s_or_b64 exec, exec, s[46:47]
	s_barrier
	ds_write_b16 v128, v48
	ds_write_b16_d16_hi v128, v48 offset:272
	ds_write_b16 v128, v50 offset:544
	ds_write_b16_d16_hi v128, v50 offset:816
	ds_write_b16 v128, v52 offset:2176
	ds_write_b16_d16_hi v128, v52 offset:2448
	ds_write_b16 v128, v54 offset:2720
	ds_write_b16_d16_hi v128, v54 offset:2992
	ds_write_b16 v128, v56 offset:4352
	ds_write_b16_d16_hi v128, v56 offset:4624
	ds_write_b16 v128, v58 offset:4896
	ds_write_b16_d16_hi v128, v58 offset:5168
	ds_write_b16 v128, v60 offset:6528
	ds_write_b16_d16_hi v128, v60 offset:6800
	ds_write_b16 v128, v62 offset:7072
	ds_write_b16_d16_hi v128, v62 offset:7344
	ds_write_b16 v128, v32 offset:64
	ds_write_b16_d16_hi v128, v32 offset:336
	ds_write_b16 v128, v34 offset:608
	ds_write_b16_d16_hi v128, v34 offset:880
	ds_write_b16 v128, v36 offset:2240
	ds_write_b16_d16_hi v128, v36 offset:2512
	ds_write_b16 v128, v38 offset:2784
	ds_write_b16_d16_hi v128, v38 offset:3056
	ds_write_b16 v128, v40 offset:4416
	ds_write_b16_d16_hi v128, v40 offset:4688
	ds_write_b16 v128, v42 offset:4960
	ds_write_b16_d16_hi v128, v42 offset:5232
	ds_write_b16 v128, v44 offset:6592
	ds_write_b16_d16_hi v128, v44 offset:6864
	ds_write_b16 v128, v46 offset:7136
	ds_write_b16_d16_hi v128, v46 offset:7408
	ds_write_b16 v128, v16 offset:8704
	ds_write_b16_d16_hi v128, v16 offset:8976
	ds_write_b16 v128, v18 offset:9248
	ds_write_b16_d16_hi v128, v18 offset:9520
	ds_write_b16 v128, v20 offset:10880
	ds_write_b16_d16_hi v128, v20 offset:11152
	ds_write_b16 v128, v22 offset:11424
	ds_write_b16_d16_hi v128, v22 offset:11696
	ds_write_b16 v128, v24 offset:13056
	ds_write_b16_d16_hi v128, v24 offset:13328
	ds_write_b16 v128, v26 offset:13600
	ds_write_b16_d16_hi v128, v26 offset:13872
	ds_write_b16 v128, v28 offset:15232
	ds_write_b16_d16_hi v128, v28 offset:15504
	ds_write_b16 v128, v30 offset:15776
	ds_write_b16_d16_hi v128, v30 offset:16048
	ds_write_b16 v128, v0 offset:8768
	ds_write_b16_d16_hi v128, v0 offset:9040
	ds_write_b16 v128, v2 offset:9312
	ds_write_b16_d16_hi v128, v2 offset:9584
	ds_write_b16 v128, v4 offset:10944
	ds_write_b16_d16_hi v128, v4 offset:11216
	ds_write_b16 v128, v6 offset:11488
	ds_write_b16_d16_hi v128, v6 offset:11760
	ds_write_b16 v128, v8 offset:13120
	ds_write_b16_d16_hi v128, v8 offset:13392
	ds_write_b16 v128, v10 offset:13664
	ds_write_b16_d16_hi v128, v10 offset:13936
	ds_write_b16 v128, v12 offset:15296
	ds_write_b16_d16_hi v128, v12 offset:15568
	ds_write_b16 v128, v14 offset:15840
	ds_write_b16_d16_hi v128, v14 offset:16112
	s_waitcnt lgkmcnt(0)
	s_barrier
	ds_read_b128 v[132:135], v129
	ds_read_b128 v[136:139], v129 offset:4352
	ds_read_b128 v[140:143], v129 offset:8704
	ds_read_b128 v[144:147], v129 offset:13056
	ds_read_b128 v[148:151], v129 offset:17408
	ds_read_b128 v[152:155], v129 offset:21760
	ds_read_b128 v[156:159], v129 offset:26112
	ds_read_b128 v[160:163], v129 offset:30464
	v_add_u32_e32 v164, 0x49000, v164
	v_add_u32_e32 v165, 0x49000, v165
	v_add_u32_e32 v166, 0x49000, v166
	v_add_u32_e32 v167, 0x49000, v167
	v_add_u32_e32 v168, 0x49000, v168
	v_add_u32_e32 v169, 0x49000, v169
	v_add_u32_e32 v170, 0x49000, v170
	v_add_u32_e32 v171, 0x49000, v171
	s_and_saveexec_b64 s[46:47], s[44:45]
	s_waitcnt lgkmcnt(7)
	global_store_dwordx4 v164, v[132:135], s[42:43]
	s_waitcnt lgkmcnt(6)
	global_store_dwordx4 v165, v[136:139], s[42:43]
	s_waitcnt lgkmcnt(5)
	global_store_dwordx4 v166, v[140:143], s[42:43]
	s_waitcnt lgkmcnt(4)
	global_store_dwordx4 v167, v[144:147], s[42:43]
	s_waitcnt lgkmcnt(3)
	global_store_dwordx4 v168, v[148:151], s[42:43]
	s_waitcnt lgkmcnt(2)
	global_store_dwordx4 v169, v[152:155], s[42:43]
	s_waitcnt lgkmcnt(1)
	global_store_dwordx4 v170, v[156:159], s[42:43]
	s_waitcnt lgkmcnt(0)
	global_store_dwordx4 v171, v[160:163], s[42:43]
	s_or_b64 exec, exec, s[46:47]
	s_branch .LBB0_1281

.LBB0_1977:
	ds_read_b128 v[216:219], v188 offset:36864
	ds_read_b128 v[200:203], v187
	ds_read_b128 v[220:223], v188 offset:41472
	ds_read_b128 v[204:207], v187 offset:4608
	ds_read_b128 v[208:211], v187 offset:9216
	ds_read_b128 v[212:215], v176
	s_waitcnt lgkmcnt(4)
	v_mfma_f32_32x32x16_bf16 v[112:127], v[200:203], v[216:219], v[112:127]
	ds_read_b128 v[240:243], v188 offset:36896
	global_load_dwordx4 v[152:155], v190, s[40:41]
	s_waitcnt lgkmcnt(4)
	v_mfma_f32_32x32x16_bf16 v[96:111], v[200:203], v[220:223], v[96:111]
	ds_read_b128 v[224:227], v187 offset:32
	global_load_dwordx4 v[164:167], v191, s[40:41]
	s_waitcnt lgkmcnt(4)
	v_mfma_f32_32x32x16_bf16 v[80:95], v[204:207], v[216:219], v[80:95]
	ds_read_b128 v[244:247], v188 offset:41504
	global_load_dwordx4 v[168:171], v192, s[40:41]
	s_waitcnt lgkmcnt(5)
	v_mfma_f32_32x32x16_bf16 v[64:79], v[204:207], v[220:223], v[64:79]
	ds_read_b128 v[228:231], v187 offset:4640
	global_load_dwordx4 v[172:175], v193, s[40:41]
	s_waitcnt lgkmcnt(5)
	v_mfma_f32_32x32x16_bf16 v[48:63], v[208:211], v[216:219], v[48:63]
	ds_read_b128 v[232:235], v187 offset:9248
	global_load_dwordx4 v[160:163], v190, s[38:39]
	s_waitcnt lgkmcnt(6)
	v_mfma_f32_32x32x16_bf16 v[32:47], v[208:211], v[220:223], v[32:47]
	ds_read_b128 v[236:239], v176 offset:32
	global_load_dwordx4 v[128:131], v191, s[38:39]
	s_waitcnt lgkmcnt(6)
	v_mfma_f32_32x32x16_bf16 v[16:31], v[212:215], v[216:219], v[16:31]
	global_load_dwordx4 v[132:135], v192, s[38:39]
	s_waitcnt lgkmcnt(6)
	v_mfma_f32_32x32x16_bf16 v[0:15], v[212:215], v[220:223], v[0:15]
	global_load_dwordx4 v[136:139], v193, s[38:39]
	s_waitcnt lgkmcnt(4)
	v_mfma_f32_32x32x16_bf16 v[112:127], v[224:227], v[240:243], v[112:127]
	ds_read_b128 v[200:203], v187 offset:64
	global_load_dwordx4 v[140:143], v194, s[38:39]
	s_waitcnt lgkmcnt(4)
	v_mfma_f32_32x32x16_bf16 v[96:111], v[224:227], v[244:247], v[96:111]
	ds_read_b128 v[204:207], v187 offset:4672
	global_load_dwordx4 v[144:147], v195, s[38:39]
	s_waitcnt lgkmcnt(4)
	v_mfma_f32_32x32x16_bf16 v[80:95], v[228:231], v[240:243], v[80:95]
	ds_read_b128 v[208:211], v187 offset:9280
	global_load_dwordx4 v[148:151], v196, s[38:39]
	s_waitcnt lgkmcnt(5)
	v_mfma_f32_32x32x16_bf16 v[64:79], v[228:231], v[244:247], v[64:79]
	ds_read_b128 v[212:215], v176 offset:64
	global_load_dwordx4 v[156:159], v197, s[38:39]
	s_add_u32 s38, s38, 0x80
	s_addc_u32 s39, s39, 0
	s_add_u32 s40, s40, 0x80
	s_addc_u32 s41, s41, 0
	s_add_u32 s12, s12, 0x80
	s_waitcnt lgkmcnt(5)
	v_mfma_f32_32x32x16_bf16 v[48:63], v[232:235], v[240:243], v[48:63]
	ds_read_b128 v[216:219], v188 offset:36928
	s_waitcnt lgkmcnt(6)
	v_mfma_f32_32x32x16_bf16 v[32:47], v[232:235], v[244:247], v[32:47]
	ds_read_b128 v[220:223], v188 offset:41536
	s_waitcnt lgkmcnt(6)
	v_mfma_f32_32x32x16_bf16 v[16:31], v[236:239], v[240:243], v[16:31]
	s_waitcnt lgkmcnt(6)
	v_mfma_f32_32x32x16_bf16 v[0:15], v[236:239], v[244:247], v[0:15]
	s_waitcnt lgkmcnt(1)
	v_mfma_f32_32x32x16_bf16 v[112:127], v[200:203], v[216:219], v[112:127]
	ds_read_b128 v[224:227], v187 offset:96
	s_waitcnt lgkmcnt(1)
	v_mfma_f32_32x32x16_bf16 v[96:111], v[200:203], v[220:223], v[96:111]
	ds_read_b128 v[228:231], v187 offset:4704
	s_waitcnt lgkmcnt(3)
	v_mfma_f32_32x32x16_bf16 v[80:95], v[204:207], v[216:219], v[80:95]
	ds_read_b128 v[232:235], v187 offset:9312
	s_waitcnt lgkmcnt(3)
	v_mfma_f32_32x32x16_bf16 v[64:79], v[204:207], v[220:223], v[64:79]
	ds_read_b128 v[236:239], v176 offset:96
	s_waitcnt lgkmcnt(5)
	v_mfma_f32_32x32x16_bf16 v[48:63], v[208:211], v[216:219], v[48:63]
	ds_read_b128 v[240:243], v188 offset:36960
	s_waitcnt lgkmcnt(5)
	v_mfma_f32_32x32x16_bf16 v[32:47], v[208:211], v[220:223], v[32:47]
	ds_read_b128 v[244:247], v188 offset:41568
	s_waitcnt lgkmcnt(7)
	v_mfma_f32_32x32x16_bf16 v[16:31], v[212:215], v[216:219], v[16:31]
	s_waitcnt lgkmcnt(6)
	v_mfma_f32_32x32x16_bf16 v[0:15], v[212:215], v[220:223], v[0:15]
	s_waitcnt lgkmcnt(0)
	s_barrier
	s_waitcnt vmcnt(0)
	s_waitcnt lgkmcnt(1)
	v_mfma_f32_32x32x16_bf16 v[112:127], v[224:227], v[240:243], v[112:127]
	ds_write_b128 v189, v[160:163]
	ds_write_b128 v189, v[128:131] offset:4608
	s_waitcnt lgkmcnt(2)
	v_mfma_f32_32x32x16_bf16 v[96:111], v[224:227], v[244:247], v[96:111]
	ds_write_b128 v189, v[132:135] offset:9216
	s_waitcnt lgkmcnt(4)
	v_mfma_f32_32x32x16_bf16 v[80:95], v[228:231], v[240:243], v[80:95]
	ds_write_b128 v189, v[136:139] offset:13824
	ds_write_b128 v189, v[140:143] offset:18432
	s_waitcnt lgkmcnt(5)
	v_mfma_f32_32x32x16_bf16 v[64:79], v[228:231], v[244:247], v[64:79]
	ds_write_b128 v189, v[144:147] offset:23040
	s_waitcnt lgkmcnt(7)
	v_mfma_f32_32x32x16_bf16 v[48:63], v[232:235], v[240:243], v[48:63]
	ds_write_b128 v189, v[148:151] offset:27648
	ds_write_b128 v189, v[156:159] offset:32256
	s_waitcnt lgkmcnt(8)
	v_mfma_f32_32x32x16_bf16 v[32:47], v[232:235], v[244:247], v[32:47]
	ds_write_b128 v189, v[152:155] offset:36864
	s_waitcnt lgkmcnt(10)
	v_mfma_f32_32x32x16_bf16 v[16:31], v[236:239], v[240:243], v[16:31]
	ds_write_b128 v189, v[164:167] offset:41472
	ds_write_b128 v189, v[168:171] offset:46080
	s_waitcnt lgkmcnt(11)
	v_mfma_f32_32x32x16_bf16 v[0:15], v[236:239], v[244:247], v[0:15]
	ds_write_b128 v189, v[172:175] offset:50688
	s_waitcnt lgkmcnt(0)
	s_barrier
	s_cmpk_lg_i32 s12, 0x780
	s_cbranch_scc1 .LBB0_1977
	ds_read_b128 v[216:219], v188 offset:36864
	ds_read_b128 v[200:203], v187
	ds_read_b128 v[220:223], v188 offset:41472
	ds_read_b128 v[204:207], v187 offset:4608
	ds_read_b128 v[208:211], v187 offset:9216
	ds_read_b128 v[212:215], v176
	s_waitcnt lgkmcnt(4)
	v_mfma_f32_32x32x16_bf16 v[112:127], v[200:203], v[216:219], v[112:127]
	ds_read_b128 v[240:243], v188 offset:36896
	s_waitcnt lgkmcnt(4)
	v_mfma_f32_32x32x16_bf16 v[96:111], v[200:203], v[220:223], v[96:111]
	ds_read_b128 v[224:227], v187 offset:32
	s_waitcnt lgkmcnt(4)
	v_mfma_f32_32x32x16_bf16 v[80:95], v[204:207], v[216:219], v[80:95]
	ds_read_b128 v[244:247], v188 offset:41504
	s_waitcnt lgkmcnt(5)
	v_mfma_f32_32x32x16_bf16 v[64:79], v[204:207], v[220:223], v[64:79]
	ds_read_b128 v[228:231], v187 offset:4640
	s_waitcnt lgkmcnt(5)
	v_mfma_f32_32x32x16_bf16 v[48:63], v[208:211], v[216:219], v[48:63]
	ds_read_b128 v[232:235], v187 offset:9248
	s_waitcnt lgkmcnt(6)
	v_mfma_f32_32x32x16_bf16 v[32:47], v[208:211], v[220:223], v[32:47]
	ds_read_b128 v[236:239], v176 offset:32
	s_waitcnt lgkmcnt(6)
	v_mfma_f32_32x32x16_bf16 v[16:31], v[212:215], v[216:219], v[16:31]
	s_waitcnt lgkmcnt(6)
	v_mfma_f32_32x32x16_bf16 v[0:15], v[212:215], v[220:223], v[0:15]
	s_waitcnt lgkmcnt(4)
	v_mfma_f32_32x32x16_bf16 v[112:127], v[224:227], v[240:243], v[112:127]
	ds_read_b128 v[200:203], v187 offset:64
	s_waitcnt lgkmcnt(4)
	v_mfma_f32_32x32x16_bf16 v[96:111], v[224:227], v[244:247], v[96:111]
	ds_read_b128 v[204:207], v187 offset:4672
	s_waitcnt lgkmcnt(4)
	v_mfma_f32_32x32x16_bf16 v[80:95], v[228:231], v[240:243], v[80:95]
	ds_read_b128 v[208:211], v187 offset:9280
	s_waitcnt lgkmcnt(5)
	v_mfma_f32_32x32x16_bf16 v[64:79], v[228:231], v[244:247], v[64:79]
	ds_read_b128 v[212:215], v176 offset:64
	s_waitcnt lgkmcnt(5)
	v_mfma_f32_32x32x16_bf16 v[48:63], v[232:235], v[240:243], v[48:63]
	ds_read_b128 v[216:219], v188 offset:36928
	s_waitcnt lgkmcnt(6)
	v_mfma_f32_32x32x16_bf16 v[32:47], v[232:235], v[244:247], v[32:47]
	ds_read_b128 v[220:223], v188 offset:41536
	s_waitcnt lgkmcnt(6)
	v_mfma_f32_32x32x16_bf16 v[16:31], v[236:239], v[240:243], v[16:31]
	s_waitcnt lgkmcnt(6)
	v_mfma_f32_32x32x16_bf16 v[0:15], v[236:239], v[244:247], v[0:15]
	s_waitcnt lgkmcnt(1)
	v_mfma_f32_32x32x16_bf16 v[112:127], v[200:203], v[216:219], v[112:127]
	ds_read_b128 v[224:227], v187 offset:96
	s_waitcnt lgkmcnt(1)
	v_mfma_f32_32x32x16_bf16 v[96:111], v[200:203], v[220:223], v[96:111]
	ds_read_b128 v[228:231], v187 offset:4704
	s_waitcnt lgkmcnt(3)
	v_mfma_f32_32x32x16_bf16 v[80:95], v[204:207], v[216:219], v[80:95]
	ds_read_b128 v[232:235], v187 offset:9312
	s_waitcnt lgkmcnt(3)
	v_mfma_f32_32x32x16_bf16 v[64:79], v[204:207], v[220:223], v[64:79]
	ds_read_b128 v[236:239], v176 offset:96
	s_waitcnt lgkmcnt(5)
	v_mfma_f32_32x32x16_bf16 v[48:63], v[208:211], v[216:219], v[48:63]
	ds_read_b128 v[240:243], v188 offset:36960
	s_waitcnt lgkmcnt(5)
	v_mfma_f32_32x32x16_bf16 v[32:47], v[208:211], v[220:223], v[32:47]
	ds_read_b128 v[244:247], v188 offset:41568
	s_waitcnt lgkmcnt(7)
	v_mfma_f32_32x32x16_bf16 v[16:31], v[212:215], v[216:219], v[16:31]
	s_waitcnt lgkmcnt(6)
	v_mfma_f32_32x32x16_bf16 v[0:15], v[212:215], v[220:223], v[0:15]
	s_waitcnt lgkmcnt(1)
	v_mfma_f32_32x32x16_bf16 v[112:127], v[224:227], v[240:243], v[112:127]
	s_waitcnt lgkmcnt(0)
	v_mfma_f32_32x32x16_bf16 v[96:111], v[224:227], v[244:247], v[96:111]
	s_waitcnt lgkmcnt(1)
	v_mfma_f32_32x32x16_bf16 v[80:95], v[228:231], v[240:243], v[80:95]
	s_waitcnt lgkmcnt(0)
	v_mfma_f32_32x32x16_bf16 v[64:79], v[228:231], v[244:247], v[64:79]
	s_waitcnt lgkmcnt(1)
	v_mfma_f32_32x32x16_bf16 v[48:63], v[232:235], v[240:243], v[48:63]
	s_waitcnt lgkmcnt(0)
	v_mfma_f32_32x32x16_bf16 v[32:47], v[232:235], v[244:247], v[32:47]
	s_waitcnt lgkmcnt(1)
	v_mfma_f32_32x32x16_bf16 v[16:31], v[236:239], v[240:243], v[16:31]
	s_waitcnt lgkmcnt(0)
	v_mfma_f32_32x32x16_bf16 v[0:15], v[236:239], v[244:247], v[0:15]
	s_mul_i32 s42, s6, 0x2000
	s_add_u32 s44, s30, s42
	s_addc_u32 s45, s31, 0
	s_lshl_b32 s42, s58, 1
	s_add_u32 s44, s44, s42
	s_addc_u32 s45, s45, 0
	s_add_u32 s44, s44, 0x7157900
	s_addc_u32 s45, s45, 0
	s_mov_b32 s43, 1
	v_max_f32_e32 v112, 0, v112
	v_max_f32_e32 v113, 0, v113
	v_mul_f32_e32 v112, v112, v112
	v_mul_f32_e32 v113, v113, v113
	v_cvt_pk_bf16_f32 v190, v112, v113
	v_max_f32_e32 v114, 0, v114
	v_max_f32_e32 v115, 0, v115
	v_mul_f32_e32 v114, v114, v114
	v_mul_f32_e32 v115, v115, v115
	v_cvt_pk_bf16_f32 v191, v114, v115
	v_max_f32_e32 v116, 0, v116
	v_max_f32_e32 v117, 0, v117
	v_mul_f32_e32 v116, v116, v116
	v_mul_f32_e32 v117, v117, v117
	v_cvt_pk_bf16_f32 v192, v116, v117
	v_max_f32_e32 v118, 0, v118
	v_max_f32_e32 v119, 0, v119
	v_mul_f32_e32 v118, v118, v118
	v_mul_f32_e32 v119, v119, v119
	v_cvt_pk_bf16_f32 v193, v118, v119
	v_max_f32_e32 v120, 0, v120
	v_max_f32_e32 v121, 0, v121
	v_mul_f32_e32 v120, v120, v120
	v_mul_f32_e32 v121, v121, v121
	v_cvt_pk_bf16_f32 v194, v120, v121
	v_max_f32_e32 v122, 0, v122
	v_max_f32_e32 v123, 0, v123
	v_mul_f32_e32 v122, v122, v122
	v_mul_f32_e32 v123, v123, v123
	v_cvt_pk_bf16_f32 v195, v122, v123
	v_max_f32_e32 v124, 0, v124
	v_max_f32_e32 v125, 0, v125
	v_mul_f32_e32 v124, v124, v124
	v_mul_f32_e32 v125, v125, v125
	v_cvt_pk_bf16_f32 v196, v124, v125
	v_max_f32_e32 v126, 0, v126
	v_max_f32_e32 v127, 0, v127
	v_mul_f32_e32 v126, v126, v126
	v_mul_f32_e32 v127, v127, v127
	v_cvt_pk_bf16_f32 v197, v126, v127
	v_max_f32_e32 v96, 0, v96
	v_max_f32_e32 v97, 0, v97
	v_mul_f32_e32 v96, v96, v96
	v_mul_f32_e32 v97, v97, v97
	v_cvt_pk_bf16_f32 v198, v96, v97
	v_max_f32_e32 v98, 0, v98
	v_max_f32_e32 v99, 0, v99
	v_mul_f32_e32 v98, v98, v98
	v_mul_f32_e32 v99, v99, v99
	v_cvt_pk_bf16_f32 v199, v98, v99
	v_max_f32_e32 v100, 0, v100
	v_max_f32_e32 v101, 0, v101
	v_mul_f32_e32 v100, v100, v100
	v_mul_f32_e32 v101, v101, v101
	v_cvt_pk_bf16_f32 v200, v100, v101
	v_max_f32_e32 v102, 0, v102
	v_max_f32_e32 v103, 0, v103
	v_mul_f32_e32 v102, v102, v102
	v_mul_f32_e32 v103, v103, v103
	v_cvt_pk_bf16_f32 v201, v102, v103
	v_max_f32_e32 v104, 0, v104
	v_max_f32_e32 v105, 0, v105
	v_mul_f32_e32 v104, v104, v104
	v_mul_f32_e32 v105, v105, v105
	v_cvt_pk_bf16_f32 v202, v104, v105
	v_max_f32_e32 v106, 0, v106
	v_max_f32_e32 v107, 0, v107
	v_mul_f32_e32 v106, v106, v106
	v_mul_f32_e32 v107, v107, v107
	v_cvt_pk_bf16_f32 v203, v106, v107
	v_max_f32_e32 v108, 0, v108
	v_max_f32_e32 v109, 0, v109
	v_mul_f32_e32 v108, v108, v108
	v_mul_f32_e32 v109, v109, v109
	v_cvt_pk_bf16_f32 v204, v108, v109
	v_max_f32_e32 v110, 0, v110
	v_max_f32_e32 v111, 0, v111
	v_mul_f32_e32 v110, v110, v110
	v_mul_f32_e32 v111, v111, v111
	v_cvt_pk_bf16_f32 v205, v110, v111
	v_max_f32_e32 v80, 0, v80
	v_max_f32_e32 v81, 0, v81
	v_mul_f32_e32 v80, v80, v80
	v_mul_f32_e32 v81, v81, v81
	v_cvt_pk_bf16_f32 v206, v80, v81
	v_max_f32_e32 v82, 0, v82
	v_max_f32_e32 v83, 0, v83
	v_mul_f32_e32 v82, v82, v82
	v_mul_f32_e32 v83, v83, v83
	v_cvt_pk_bf16_f32 v207, v82, v83
	v_max_f32_e32 v84, 0, v84
	v_max_f32_e32 v85, 0, v85
	v_mul_f32_e32 v84, v84, v84
	v_mul_f32_e32 v85, v85, v85
	v_cvt_pk_bf16_f32 v208, v84, v85
	v_max_f32_e32 v86, 0, v86
	v_max_f32_e32 v87, 0, v87
	v_mul_f32_e32 v86, v86, v86
	v_mul_f32_e32 v87, v87, v87
	v_cvt_pk_bf16_f32 v209, v86, v87
	v_max_f32_e32 v88, 0, v88
	v_max_f32_e32 v89, 0, v89
	v_mul_f32_e32 v88, v88, v88
	v_mul_f32_e32 v89, v89, v89
	v_cvt_pk_bf16_f32 v210, v88, v89
	v_max_f32_e32 v90, 0, v90
	v_max_f32_e32 v91, 0, v91
	v_mul_f32_e32 v90, v90, v90
	v_mul_f32_e32 v91, v91, v91
	v_cvt_pk_bf16_f32 v211, v90, v91
	v_max_f32_e32 v92, 0, v92
	v_max_f32_e32 v93, 0, v93
	v_mul_f32_e32 v92, v92, v92
	v_mul_f32_e32 v93, v93, v93
	v_cvt_pk_bf16_f32 v212, v92, v93
	v_max_f32_e32 v94, 0, v94
	v_max_f32_e32 v95, 0, v95
	v_mul_f32_e32 v94, v94, v94
	v_mul_f32_e32 v95, v95, v95
	v_cvt_pk_bf16_f32 v213, v94, v95
	v_max_f32_e32 v64, 0, v64
	v_max_f32_e32 v65, 0, v65
	v_mul_f32_e32 v64, v64, v64
	v_mul_f32_e32 v65, v65, v65
	v_cvt_pk_bf16_f32 v214, v64, v65
	v_max_f32_e32 v66, 0, v66
	v_max_f32_e32 v67, 0, v67
	v_mul_f32_e32 v66, v66, v66
	v_mul_f32_e32 v67, v67, v67
	v_cvt_pk_bf16_f32 v215, v66, v67
	v_max_f32_e32 v68, 0, v68
	v_max_f32_e32 v69, 0, v69
	v_mul_f32_e32 v68, v68, v68
	v_mul_f32_e32 v69, v69, v69
	v_cvt_pk_bf16_f32 v216, v68, v69
	v_max_f32_e32 v70, 0, v70
	v_max_f32_e32 v71, 0, v71
	v_mul_f32_e32 v70, v70, v70
	v_mul_f32_e32 v71, v71, v71
	v_cvt_pk_bf16_f32 v217, v70, v71
	v_max_f32_e32 v72, 0, v72
	v_max_f32_e32 v73, 0, v73
	v_mul_f32_e32 v72, v72, v72
	v_mul_f32_e32 v73, v73, v73
	v_cvt_pk_bf16_f32 v218, v72, v73
	v_max_f32_e32 v74, 0, v74
	v_max_f32_e32 v75, 0, v75
	v_mul_f32_e32 v74, v74, v74
	v_mul_f32_e32 v75, v75, v75
	v_cvt_pk_bf16_f32 v219, v74, v75
	v_max_f32_e32 v76, 0, v76
	v_max_f32_e32 v77, 0, v77
	v_mul_f32_e32 v76, v76, v76
	v_mul_f32_e32 v77, v77, v77
	v_cvt_pk_bf16_f32 v220, v76, v77
	v_max_f32_e32 v78, 0, v78
	v_max_f32_e32 v79, 0, v79
	v_mul_f32_e32 v78, v78, v78
	v_mul_f32_e32 v79, v79, v79
	v_cvt_pk_bf16_f32 v221, v78, v79
	v_max_f32_e32 v48, 0, v48
	v_max_f32_e32 v49, 0, v49
	v_mul_f32_e32 v48, v48, v48
	v_mul_f32_e32 v49, v49, v49
	v_cvt_pk_bf16_f32 v222, v48, v49
	v_max_f32_e32 v50, 0, v50
	v_max_f32_e32 v51, 0, v51
	v_mul_f32_e32 v50, v50, v50
	v_mul_f32_e32 v51, v51, v51
	v_cvt_pk_bf16_f32 v223, v50, v51
	v_max_f32_e32 v52, 0, v52
	v_max_f32_e32 v53, 0, v53
	v_mul_f32_e32 v52, v52, v52
	v_mul_f32_e32 v53, v53, v53
	v_cvt_pk_bf16_f32 v224, v52, v53
	v_max_f32_e32 v54, 0, v54
	v_max_f32_e32 v55, 0, v55
	v_mul_f32_e32 v54, v54, v54
	v_mul_f32_e32 v55, v55, v55
	v_cvt_pk_bf16_f32 v225, v54, v55
	v_max_f32_e32 v56, 0, v56
	v_max_f32_e32 v57, 0, v57
	v_mul_f32_e32 v56, v56, v56
	v_mul_f32_e32 v57, v57, v57
	v_cvt_pk_bf16_f32 v226, v56, v57
	v_max_f32_e32 v58, 0, v58
	v_max_f32_e32 v59, 0, v59
	v_mul_f32_e32 v58, v58, v58
	v_mul_f32_e32 v59, v59, v59
	v_cvt_pk_bf16_f32 v227, v58, v59
	v_max_f32_e32 v60, 0, v60
	v_max_f32_e32 v61, 0, v61
	v_mul_f32_e32 v60, v60, v60
	v_mul_f32_e32 v61, v61, v61
	v_cvt_pk_bf16_f32 v228, v60, v61
	v_max_f32_e32 v62, 0, v62
	v_max_f32_e32 v63, 0, v63
	v_mul_f32_e32 v62, v62, v62
	v_mul_f32_e32 v63, v63, v63
	v_cvt_pk_bf16_f32 v229, v62, v63
	v_max_f32_e32 v32, 0, v32
	v_max_f32_e32 v33, 0, v33
	v_mul_f32_e32 v32, v32, v32
	v_mul_f32_e32 v33, v33, v33
	v_cvt_pk_bf16_f32 v230, v32, v33
	v_max_f32_e32 v34, 0, v34
	v_max_f32_e32 v35, 0, v35
	v_mul_f32_e32 v34, v34, v34
	v_mul_f32_e32 v35, v35, v35
	v_cvt_pk_bf16_f32 v231, v34, v35
	v_max_f32_e32 v36, 0, v36
	v_max_f32_e32 v37, 0, v37
	v_mul_f32_e32 v36, v36, v36
	v_mul_f32_e32 v37, v37, v37
	v_cvt_pk_bf16_f32 v232, v36, v37
	v_max_f32_e32 v38, 0, v38
	v_max_f32_e32 v39, 0, v39
	v_mul_f32_e32 v38, v38, v38
	v_mul_f32_e32 v39, v39, v39
	v_cvt_pk_bf16_f32 v233, v38, v39
	v_max_f32_e32 v40, 0, v40
	v_max_f32_e32 v41, 0, v41
	v_mul_f32_e32 v40, v40, v40
	v_mul_f32_e32 v41, v41, v41
	v_cvt_pk_bf16_f32 v234, v40, v41
	v_max_f32_e32 v42, 0, v42
	v_max_f32_e32 v43, 0, v43
	v_mul_f32_e32 v42, v42, v42
	v_mul_f32_e32 v43, v43, v43
	v_cvt_pk_bf16_f32 v235, v42, v43
	v_max_f32_e32 v44, 0, v44
	v_max_f32_e32 v45, 0, v45
	v_mul_f32_e32 v44, v44, v44
	v_mul_f32_e32 v45, v45, v45
	v_cvt_pk_bf16_f32 v236, v44, v45
	v_max_f32_e32 v46, 0, v46
	v_max_f32_e32 v47, 0, v47
	v_mul_f32_e32 v46, v46, v46
	v_mul_f32_e32 v47, v47, v47
	v_cvt_pk_bf16_f32 v237, v46, v47
	v_max_f32_e32 v16, 0, v16
	v_max_f32_e32 v17, 0, v17
	v_mul_f32_e32 v16, v16, v16
	v_mul_f32_e32 v17, v17, v17
	v_cvt_pk_bf16_f32 v238, v16, v17
	v_max_f32_e32 v18, 0, v18
	v_max_f32_e32 v19, 0, v19
	v_mul_f32_e32 v18, v18, v18
	v_mul_f32_e32 v19, v19, v19
	v_cvt_pk_bf16_f32 v239, v18, v19
	v_max_f32_e32 v20, 0, v20
	v_max_f32_e32 v21, 0, v21
	v_mul_f32_e32 v20, v20, v20
	v_mul_f32_e32 v21, v21, v21
	v_cvt_pk_bf16_f32 v240, v20, v21
	v_max_f32_e32 v22, 0, v22
	v_max_f32_e32 v23, 0, v23
	v_mul_f32_e32 v22, v22, v22
	v_mul_f32_e32 v23, v23, v23
	v_cvt_pk_bf16_f32 v241, v22, v23
	v_max_f32_e32 v24, 0, v24
	v_max_f32_e32 v25, 0, v25
	v_mul_f32_e32 v24, v24, v24
	v_mul_f32_e32 v25, v25, v25
	v_cvt_pk_bf16_f32 v242, v24, v25
	v_max_f32_e32 v26, 0, v26
	v_max_f32_e32 v27, 0, v27
	v_mul_f32_e32 v26, v26, v26
	v_mul_f32_e32 v27, v27, v27
	v_cvt_pk_bf16_f32 v243, v26, v27
	v_max_f32_e32 v28, 0, v28
	v_max_f32_e32 v29, 0, v29
	v_mul_f32_e32 v28, v28, v28
	v_mul_f32_e32 v29, v29, v29
	v_cvt_pk_bf16_f32 v244, v28, v29
	v_max_f32_e32 v30, 0, v30
	v_max_f32_e32 v31, 0, v31
	v_mul_f32_e32 v30, v30, v30
	v_mul_f32_e32 v31, v31, v31
	v_cvt_pk_bf16_f32 v245, v30, v31
	v_max_f32_e32 v0, 0, v0
	v_max_f32_e32 v1, 0, v1
	v_mul_f32_e32 v0, v0, v0
	v_mul_f32_e32 v1, v1, v1
	v_cvt_pk_bf16_f32 v246, v0, v1
	v_max_f32_e32 v2, 0, v2
	v_max_f32_e32 v3, 0, v3
	v_mul_f32_e32 v2, v2, v2
	v_mul_f32_e32 v3, v3, v3
	v_cvt_pk_bf16_f32 v247, v2, v3
	v_max_f32_e32 v4, 0, v4
	v_max_f32_e32 v5, 0, v5
	v_mul_f32_e32 v4, v4, v4
	v_mul_f32_e32 v5, v5, v5
	v_cvt_pk_bf16_f32 v248, v4, v5
	v_max_f32_e32 v6, 0, v6
	v_max_f32_e32 v7, 0, v7
	v_mul_f32_e32 v6, v6, v6
	v_mul_f32_e32 v7, v7, v7
	v_cvt_pk_bf16_f32 v249, v6, v7
	v_max_f32_e32 v8, 0, v8
	v_max_f32_e32 v9, 0, v9
	v_mul_f32_e32 v8, v8, v8
	v_mul_f32_e32 v9, v9, v9
	v_cvt_pk_bf16_f32 v250, v8, v9
	v_max_f32_e32 v10, 0, v10
	v_max_f32_e32 v11, 0, v11
	v_mul_f32_e32 v10, v10, v10
	v_mul_f32_e32 v11, v11, v11
	v_cvt_pk_bf16_f32 v251, v10, v11
	v_max_f32_e32 v12, 0, v12
	v_max_f32_e32 v13, 0, v13
	v_mul_f32_e32 v12, v12, v12
	v_mul_f32_e32 v13, v13, v13
	v_cvt_pk_bf16_f32 v252, v12, v13
	v_max_f32_e32 v14, 0, v14
	v_max_f32_e32 v15, 0, v15
	v_mul_f32_e32 v14, v14, v14
	v_mul_f32_e32 v15, v15, v15
	v_cvt_pk_bf16_f32 v253, v14, v15
	s_add_i32 s57, s57, s21
	s_add_i32 s56, s56, s21
	s_cmpk_lt_u32 s57, 0x200
	s_cbranch_scc1 .LBB0_1976
	v_and_b32_e32 v3, 15, v182
	v_lshrrev_b32_e32 v4, 4, v182
	v_mul_u32_u24_e32 v2, 0x2000, v4
	v_lshl_add_u32 v2, v3, 4, v2
	v_mul_u32_u24_e32 v1, 0x110, v4
	v_lshl_add_u32 v1, v3, 4, v1
	v_lshrrev_b32_e32 v3, 7, v182
	v_bfe_u32 v4, v182, 5, 1
	v_lshlrev_b32_e32 v3, 6, v3
	v_lshl_or_b32 v3, v4, 2, v3
	v_mul_u32_u24_e32 v3, 136, v3
	v_and_b32_e32 v4, 0x5f, v182
	v_add_lshl_u32 v0, v3, v4, 1
	s_barrier
	ds_write_b16 v0, v190
	ds_write_b16_d16_hi v0, v190 offset:272
	ds_write_b16 v0, v191 offset:544
	ds_write_b16_d16_hi v0, v191 offset:816
	ds_write_b16 v0, v192 offset:2176
	ds_write_b16_d16_hi v0, v192 offset:2448
	ds_write_b16 v0, v193 offset:2720
	ds_write_b16_d16_hi v0, v193 offset:2992
	ds_write_b16 v0, v194 offset:4352
	ds_write_b16_d16_hi v0, v194 offset:4624
	ds_write_b16 v0, v195 offset:4896
	ds_write_b16_d16_hi v0, v195 offset:5168
	ds_write_b16 v0, v196 offset:6528
	ds_write_b16_d16_hi v0, v196 offset:6800
	ds_write_b16 v0, v197 offset:7072
	ds_write_b16_d16_hi v0, v197 offset:7344
	ds_write_b16 v0, v198 offset:64
	ds_write_b16_d16_hi v0, v198 offset:336
	ds_write_b16 v0, v199 offset:608
	ds_write_b16_d16_hi v0, v199 offset:880
	ds_write_b16 v0, v200 offset:2240
	ds_write_b16_d16_hi v0, v200 offset:2512
	ds_write_b16 v0, v201 offset:2784
	ds_write_b16_d16_hi v0, v201 offset:3056
	ds_write_b16 v0, v202 offset:4416
	ds_write_b16_d16_hi v0, v202 offset:4688
	ds_write_b16 v0, v203 offset:4960
	ds_write_b16_d16_hi v0, v203 offset:5232
	ds_write_b16 v0, v204 offset:6592
	ds_write_b16_d16_hi v0, v204 offset:6864
	ds_write_b16 v0, v205 offset:7136
	ds_write_b16_d16_hi v0, v205 offset:7408
	ds_write_b16 v0, v206 offset:8704
	ds_write_b16_d16_hi v0, v206 offset:8976
	ds_write_b16 v0, v207 offset:9248
	ds_write_b16_d16_hi v0, v207 offset:9520
	ds_write_b16 v0, v208 offset:10880
	ds_write_b16_d16_hi v0, v208 offset:11152
	ds_write_b16 v0, v209 offset:11424
	ds_write_b16_d16_hi v0, v209 offset:11696
	ds_write_b16 v0, v210 offset:13056
	ds_write_b16_d16_hi v0, v210 offset:13328
	ds_write_b16 v0, v211 offset:13600
	ds_write_b16_d16_hi v0, v211 offset:13872
	ds_write_b16 v0, v212 offset:15232
	ds_write_b16_d16_hi v0, v212 offset:15504
	ds_write_b16 v0, v213 offset:15776
	ds_write_b16_d16_hi v0, v213 offset:16048
	ds_write_b16 v0, v214 offset:8768
	ds_write_b16_d16_hi v0, v214 offset:9040
	ds_write_b16 v0, v215 offset:9312
	ds_write_b16_d16_hi v0, v215 offset:9584
	ds_write_b16 v0, v216 offset:10944
	ds_write_b16_d16_hi v0, v216 offset:11216
	ds_write_b16 v0, v217 offset:11488
	ds_write_b16_d16_hi v0, v217 offset:11760
	ds_write_b16 v0, v218 offset:13120
	ds_write_b16_d16_hi v0, v218 offset:13392
	ds_write_b16 v0, v219 offset:13664
	ds_write_b16_d16_hi v0, v219 offset:13936
	ds_write_b16 v0, v220 offset:15296
	ds_write_b16_d16_hi v0, v220 offset:15568
	ds_write_b16 v0, v221 offset:15840
	ds_write_b16_d16_hi v0, v221 offset:16112
	s_waitcnt lgkmcnt(0)
	s_barrier
	ds_read_b128 v[8:11], v1
	ds_read_b128 v[12:15], v1 offset:4352
	ds_read_b128 v[16:19], v1 offset:8704
	ds_read_b128 v[20:23], v1 offset:13056
	ds_read_b128 v[24:27], v1 offset:17408
	ds_read_b128 v[28:31], v1 offset:21760
	ds_read_b128 v[32:35], v1 offset:26112
	ds_read_b128 v[36:39], v1 offset:30464
	s_add_u32 s38, s44, 0x0
	s_addc_u32 s39, s45, 0
	s_waitcnt lgkmcnt(7)
	global_store_dwordx4 v2, v[8:11], s[38:39]
	s_add_u32 s38, s44, 0x20000
	s_addc_u32 s39, s45, 0
	s_waitcnt lgkmcnt(6)
	global_store_dwordx4 v2, v[12:15], s[38:39]
	s_add_u32 s38, s44, 0x40000
	s_addc_u32 s39, s45, 0
	s_waitcnt lgkmcnt(5)
	global_store_dwordx4 v2, v[16:19], s[38:39]
	s_add_u32 s38, s44, 0x60000
	s_addc_u32 s39, s45, 0
	s_waitcnt lgkmcnt(4)
	global_store_dwordx4 v2, v[20:23], s[38:39]
	s_add_u32 s38, s44, 0x100000
	s_addc_u32 s39, s45, 0
	s_waitcnt lgkmcnt(3)
	global_store_dwordx4 v2, v[24:27], s[38:39]
	s_add_u32 s38, s44, 0x120000
	s_addc_u32 s39, s45, 0
	s_waitcnt lgkmcnt(2)
	global_store_dwordx4 v2, v[28:31], s[38:39]
	s_add_u32 s38, s44, 0x140000
	s_addc_u32 s39, s45, 0
	s_waitcnt lgkmcnt(1)
	global_store_dwordx4 v2, v[32:35], s[38:39]
	s_add_u32 s38, s44, 0x160000
	s_addc_u32 s39, s45, 0
	s_waitcnt lgkmcnt(0)
	global_store_dwordx4 v2, v[36:39], s[38:39]
	s_barrier
	ds_write_b16 v0, v222
	ds_write_b16_d16_hi v0, v222 offset:272
	ds_write_b16 v0, v223 offset:544
	ds_write_b16_d16_hi v0, v223 offset:816
	ds_write_b16 v0, v224 offset:2176
	ds_write_b16_d16_hi v0, v224 offset:2448
	ds_write_b16 v0, v225 offset:2720
	ds_write_b16_d16_hi v0, v225 offset:2992
	ds_write_b16 v0, v226 offset:4352
	ds_write_b16_d16_hi v0, v226 offset:4624
	ds_write_b16 v0, v227 offset:4896
	ds_write_b16_d16_hi v0, v227 offset:5168
	ds_write_b16 v0, v228 offset:6528
	ds_write_b16_d16_hi v0, v228 offset:6800
	ds_write_b16 v0, v229 offset:7072
	ds_write_b16_d16_hi v0, v229 offset:7344
	ds_write_b16 v0, v230 offset:64
	ds_write_b16_d16_hi v0, v230 offset:336
	ds_write_b16 v0, v231 offset:608
	ds_write_b16_d16_hi v0, v231 offset:880
	ds_write_b16 v0, v232 offset:2240
	ds_write_b16_d16_hi v0, v232 offset:2512
	ds_write_b16 v0, v233 offset:2784
	ds_write_b16_d16_hi v0, v233 offset:3056
	ds_write_b16 v0, v234 offset:4416
	ds_write_b16_d16_hi v0, v234 offset:4688
	ds_write_b16 v0, v235 offset:4960
	ds_write_b16_d16_hi v0, v235 offset:5232
	ds_write_b16 v0, v236 offset:6592
	ds_write_b16_d16_hi v0, v236 offset:6864
	ds_write_b16 v0, v237 offset:7136
	ds_write_b16_d16_hi v0, v237 offset:7408
	ds_write_b16 v0, v238 offset:8704
	ds_write_b16_d16_hi v0, v238 offset:8976
	ds_write_b16 v0, v239 offset:9248
	ds_write_b16_d16_hi v0, v239 offset:9520
	ds_write_b16 v0, v240 offset:10880
	ds_write_b16_d16_hi v0, v240 offset:11152
	ds_write_b16 v0, v241 offset:11424
	ds_write_b16_d16_hi v0, v241 offset:11696
	ds_write_b16 v0, v242 offset:13056
	ds_write_b16_d16_hi v0, v242 offset:13328
	ds_write_b16 v0, v243 offset:13600
	ds_write_b16_d16_hi v0, v243 offset:13872
	ds_write_b16 v0, v244 offset:15232
	ds_write_b16_d16_hi v0, v244 offset:15504
	ds_write_b16 v0, v245 offset:15776
	ds_write_b16_d16_hi v0, v245 offset:16048
	ds_write_b16 v0, v246 offset:8768
	ds_write_b16_d16_hi v0, v246 offset:9040
	ds_write_b16 v0, v247 offset:9312
	ds_write_b16_d16_hi v0, v247 offset:9584
	ds_write_b16 v0, v248 offset:10944
	ds_write_b16_d16_hi v0, v248 offset:11216
	ds_write_b16 v0, v249 offset:11488
	ds_write_b16_d16_hi v0, v249 offset:11760
	ds_write_b16 v0, v250 offset:13120
	ds_write_b16_d16_hi v0, v250 offset:13392
	ds_write_b16 v0, v251 offset:13664
	ds_write_b16_d16_hi v0, v251 offset:13936
	ds_write_b16 v0, v252 offset:15296
	ds_write_b16_d16_hi v0, v252 offset:15568
	ds_write_b16 v0, v253 offset:15840
	ds_write_b16_d16_hi v0, v253 offset:16112
	s_waitcnt lgkmcnt(0)
	s_barrier
	ds_read_b128 v[8:11], v1
	ds_read_b128 v[12:15], v1 offset:4352
	ds_read_b128 v[16:19], v1 offset:8704
	ds_read_b128 v[20:23], v1 offset:13056
	ds_read_b128 v[24:27], v1 offset:17408
	ds_read_b128 v[28:31], v1 offset:21760
	ds_read_b128 v[32:35], v1 offset:26112
	ds_read_b128 v[36:39], v1 offset:30464
	s_add_u32 s38, s44, 0x80000
	s_addc_u32 s39, s45, 0
	s_waitcnt lgkmcnt(7)
	global_store_dwordx4 v2, v[8:11], s[38:39]
	s_add_u32 s38, s44, 0xa0000
	s_addc_u32 s39, s45, 0
	s_waitcnt lgkmcnt(6)
	global_store_dwordx4 v2, v[12:15], s[38:39]
	s_add_u32 s38, s44, 0xc0000
	s_addc_u32 s39, s45, 0
	s_waitcnt lgkmcnt(5)
	global_store_dwordx4 v2, v[16:19], s[38:39]
	s_add_u32 s38, s44, 0xe0000
	s_addc_u32 s39, s45, 0
	s_waitcnt lgkmcnt(4)
	global_store_dwordx4 v2, v[20:23], s[38:39]
	s_add_u32 s38, s44, 0x180000
	s_addc_u32 s39, s45, 0
	s_waitcnt lgkmcnt(3)
	global_store_dwordx4 v2, v[24:27], s[38:39]
	s_add_u32 s38, s44, 0x1a0000
	s_addc_u32 s39, s45, 0
	s_waitcnt lgkmcnt(2)
	global_store_dwordx4 v2, v[28:31], s[38:39]
	s_add_u32 s38, s44, 0x1c0000
	s_addc_u32 s39, s45, 0
	s_waitcnt lgkmcnt(1)
	global_store_dwordx4 v2, v[32:35], s[38:39]
	s_add_u32 s38, s44, 0x1e0000
	s_addc_u32 s39, s45, 0
	s_waitcnt lgkmcnt(0)
	global_store_dwordx4 v2, v[36:39], s[38:39]
	s_mov_b32 s43, 0
	s_branch .LBB0_1969
